# dn_prep forward-substitution: A-row and rhs LDS reads renamed into rotating buffers v172-v209 and issued 6 reads ahead with exact lgkmcnt waits (on stack5)
# speedup vs baseline: 1.0050x; 1.0050x over previous
; DI void dn_prep_item(CParams& p, int layer, int it, int S, char* lds) {
;     ...
;     __syncthreads();
;     float xs[32];
; #pragma unroll
;     for (int q = 0; q < 32; ++q) xs[q] = 0.f;
;     const int c = tid >> 1, half = tid & 1;
;     {
;       const float* Rc = (c < 64) ? (RU + c) : (RW + (c - 64));
;       const float* Ah = Am + 4 * half;
; #pragma unroll
;       for (int i = 0; i < 64; ++i) {
;         float part = 0.f;
; #pragma unroll
;         for (int q = 0; q < (i + 7) / 8; ++q) {
;           const f32x4 a = *(const f32x4*)(Ah + i * 68 + 8 * q);
;           part += a[0] * xs[4 * q] + a[1] * xs[4 * q + 1] + a[2] * xs[4 * q + 2] + a[3] * xs[4 * q + 3];
;         }
;         const float other = __int_as_float(__builtin_amdgcn_update_dpp(0, __float_as_int(part), 0xB1, 0xf, 0xf, true));
;         const float xi = Rc[i * 64] - (part + other);
;         const int loc = ((i >> 3) << 2) + (i & 3);
;         if (((i >> 2) & 1) == 0) xs[loc] = (half == 0) ? xi : xs[loc];
;         else xs[loc] = (half == 1) ? xi : xs[loc];
;         if (i < 16 ? ((i & 7) == 7) : (i < 32 ? ((i & 3) == 3) : ((i & 1) == 1))) asm volatile("" ::: "memory");
;       }
;     }
.LBB0_517:
	s_or_b64 exec, exec, s[8:9]
	ds_write_b32 v0, v2 offset:46640
	s_waitcnt lgkmcnt(0)
	s_barrier
	ds_read2st64_b32 v[204:205], v42 offset1:1
	ds_read_b128 v[172:175], v43 offset:33040
	ds_read_b128 v[176:179], v43 offset:33312
	ds_read2st64_b32 v[206:207], v42 offset0:2 offset1:3
	ds_read_b128 v[180:183], v43 offset:33584
	ds_read_b128 v[184:187], v43 offset:33856
	ds_read_b128 v[188:191], v43 offset:34128
	ds_read_b128 v[192:195], v43 offset:34400
	v_mov_b32_dpp v2, v1 quad_perm:[1, 0, 3, 2] row_mask:0xf bank_mask:0xf bound_ctrl:1
	v_add_f32_e32 v2, 0, v2
	s_xor_b64 s[82:83], s[6:7], -1
	s_mov_b64 s[6:7], 0
	s_waitcnt lgkmcnt(7)
	v_sub_f32_e32 v8, v204, v2
	ds_read_b128 v[196:199], v43 offset:34672
	v_cndmask_b32_e64 v9, 0, v8, s[46:47]
	s_waitcnt lgkmcnt(7)
	v_mul_f32_e32 v2, v172, v9
	v_fmac_f32_e32 v2, 0, v173
	v_fmac_f32_e32 v2, 0, v174
	v_fmac_f32_e32 v2, 0, v175
	v_add_f32_e32 v2, 0, v2
	s_nop 1
	v_add_f32_dpp v2, v2, v2 quad_perm:[1, 0, 3, 2] row_mask:0xf bank_mask:0xf bound_ctrl:1
	v_sub_f32_e32 v10, v205, v2
	ds_read_b128 v[200:203], v43 offset:34944
	v_cndmask_b32_e64 v11, 0, v10, s[46:47]
	ds_read2st64_b32 v[208:209], v42 offset0:4 offset1:5
	s_waitcnt lgkmcnt(8)
	v_mul_f32_e32 v3, v177, v11
	v_fmac_f32_e32 v3, v9, v176
	v_fmac_f32_e32 v3, 0, v178
	v_fmac_f32_e32 v3, 0, v179
	v_add_f32_e32 v2, 0, v3
	s_nop 1
	v_add_f32_dpp v2, v2, v2 quad_perm:[1, 0, 3, 2] row_mask:0xf bank_mask:0xf bound_ctrl:1
	s_waitcnt lgkmcnt(7)
	v_sub_f32_e32 v12, v206, v2
	ds_read_b128 v[172:175], v43 offset:36032
	v_cndmask_b32_e64 v13, 0, v12, s[46:47]
	s_waitcnt lgkmcnt(7)
	v_mul_f32_e32 v3, v181, v11
	v_fmac_f32_e32 v3, v9, v180
	v_fmac_f32_e32 v3, v182, v13
	v_fmac_f32_e32 v3, 0, v183
	v_add_f32_e32 v2, 0, v3
	s_nop 1
	v_add_f32_dpp v2, v2, v2 quad_perm:[1, 0, 3, 2] row_mask:0xf bank_mask:0xf bound_ctrl:1
	v_sub_f32_e32 v14, v207, v2
	ds_read_b128 v[176:179], v43 offset:35216
	v_cndmask_b32_e64 v15, 0, v14, s[46:47]
	s_waitcnt lgkmcnt(7)
	v_mul_f32_e32 v3, v185, v11
	v_fmac_f32_e32 v3, v9, v184
	v_fmac_f32_e32 v3, v186, v13
	v_fmac_f32_e32 v3, v187, v15
	v_add_f32_e32 v4, 0, v3
	ds_read2st64_b32 v[204:205], v42 offset0:6 offset1:7
	s_nop 0
	v_add_f32_dpp v4, v4, v4 quad_perm:[1, 0, 3, 2] row_mask:0xf bank_mask:0xf bound_ctrl:1
	s_waitcnt lgkmcnt(3)
	v_sub_f32_e32 v2, v208, v4
	v_cndmask_b32_e64 v4, v2, v8, s[46:47]
	ds_read_b128 v[180:183], v43 offset:35248
	v_mul_f32_e32 v2, v188, v4
	v_fmac_f32_e32 v2, v11, v189
	v_fmac_f32_e32 v2, v190, v13
	v_fmac_f32_e32 v2, v191, v15
	ds_read_b128 v[184:187], v43 offset:35488
	v_add_f32_e32 v2, 0, v2
	s_nop 1
	v_add_f32_dpp v2, v2, v2 quad_perm:[1, 0, 3, 2] row_mask:0xf bank_mask:0xf bound_ctrl:1
	v_sub_f32_e32 v2, v209, v2
	v_cndmask_b32_e64 v5, v2, v10, s[46:47]
	v_mul_f32_e32 v2, v193, v5
	v_fmac_f32_e32 v2, v192, v4
	v_fmac_f32_e32 v2, v194, v13
	v_fmac_f32_e32 v2, v195, v15
	v_add_f32_e32 v6, 0, v2
	ds_read2st64_b32 v[206:207], v42 offset0:8 offset1:9
	ds_read_b128 v[188:191], v43 offset:35520
	v_add_f32_dpp v6, v6, v6 quad_perm:[1, 0, 3, 2] row_mask:0xf bank_mask:0xf bound_ctrl:1
	s_waitcnt lgkmcnt(4)
	v_sub_f32_e32 v2, v204, v6
	v_cndmask_b32_e64 v6, v2, v12, s[46:47]
	v_mul_f32_e32 v2, v197, v5
	v_fmac_f32_e32 v2, v196, v4
	v_fmac_f32_e32 v2, v198, v6
	v_fmac_f32_e32 v2, v199, v15
	ds_read_b128 v[192:195], v43 offset:35760
	v_add_f32_e32 v2, 0, v2
	s_nop 1
	v_add_f32_dpp v2, v2, v2 quad_perm:[1, 0, 3, 2] row_mask:0xf bank_mask:0xf bound_ctrl:1
	v_sub_f32_e32 v2, v205, v2
	v_cndmask_b32_e64 v7, v2, v14, s[46:47]
	ds_read_b128 v[196:199], v43 offset:35792
	v_mul_f32_e32 v2, v201, v5
	v_fmac_f32_e32 v2, v200, v4
	v_fmac_f32_e32 v2, v202, v6
	v_fmac_f32_e32 v2, v203, v7
	v_add_f32_e32 v8, 0, v2
	ds_read2st64_b32 v[208:209], v42 offset0:10 offset1:11
	s_nop 0
	v_add_f32_dpp v8, v8, v8 quad_perm:[1, 0, 3, 2] row_mask:0xf bank_mask:0xf bound_ctrl:1
	s_waitcnt lgkmcnt(4)
	v_sub_f32_e32 v13, v206, v8
	ds_read_b128 v[200:203], v43 offset:36064
	v_cndmask_b32_e64 v66, 0, v13, s[46:47]
	v_mul_f32_e32 v2, v177, v5
	v_fmac_f32_e32 v2, v176, v4
	v_fmac_f32_e32 v2, v178, v6
	v_fmac_f32_e32 v2, v179, v7
	ds_read_b128 v[176:179], v43 offset:36304
	v_add_f32_e32 v2, 0, v2
	v_mul_f32_e32 v8, v180, v66
	v_fmac_f32_e32 v8, 0, v181
	v_fmac_f32_e32 v8, 0, v182
	v_fmac_f32_e32 v8, 0, v183
	v_add_f32_e32 v2, v2, v8
	ds_read_b128 v[180:183], v43 offset:36336
	s_nop 0
	v_add_f32_dpp v2, v2, v2 quad_perm:[1, 0, 3, 2] row_mask:0xf bank_mask:0xf bound_ctrl:1
	v_sub_f32_e32 v67, v207, v2
	v_cndmask_b32_e64 v68, 0, v67, s[46:47]
	v_mul_f32_e32 v2, v185, v5
	v_fmac_f32_e32 v2, v184, v4
	v_fmac_f32_e32 v2, v186, v6
	v_fmac_f32_e32 v2, v187, v7
	ds_read_b128 v[184:187], v43 offset:36576
	v_add_f32_e32 v2, 0, v2
	s_waitcnt lgkmcnt(7)
	v_mul_f32_e32 v3, v189, v68
	v_fmac_f32_e32 v3, v188, v66
	v_fmac_f32_e32 v3, 0, v190
	v_fmac_f32_e32 v3, 0, v191
	v_add_f32_e32 v8, v2, v3
	ds_read2st64_b32 v[204:205], v42 offset0:12 offset1:13
	s_nop 0
	v_add_f32_dpp v8, v8, v8 quad_perm:[1, 0, 3, 2] row_mask:0xf bank_mask:0xf bound_ctrl:1
	s_waitcnt lgkmcnt(5)
	v_sub_f32_e32 v69, v208, v8
	ds_read_b128 v[188:191], v43 offset:36608
	v_cndmask_b32_e64 v70, 0, v69, s[46:47]
	v_mul_f32_e32 v2, v193, v5
	v_fmac_f32_e32 v2, v4, v192
	v_fmac_f32_e32 v2, v194, v6
	v_fmac_f32_e32 v2, v195, v7
	ds_read_b128 v[192:195], v43 offset:36848
	v_add_f32_e32 v2, 0, v2
	v_mul_f32_e32 v9, v197, v68
	v_fmac_f32_e32 v9, v196, v66
	v_fmac_f32_e32 v9, v198, v70
	v_fmac_f32_e32 v9, 0, v199
	v_add_f32_e32 v2, v2, v9
	s_nop 1
	v_add_f32_dpp v2, v2, v2 quad_perm:[1, 0, 3, 2] row_mask:0xf bank_mask:0xf bound_ctrl:1
	v_sub_f32_e32 v11, v209, v2
	v_mul_f32_e32 v2, v173, v5
	v_fmac_f32_e32 v2, v4, v172
	v_fmac_f32_e32 v2, v174, v6
	v_fmac_f32_e32 v2, v175, v7
	ds_read_b128 v[196:199], v43 offset:36880
	v_cndmask_b32_e64 v12, 0, v11, s[46:47]
	v_add_f32_e32 v2, 0, v2
	s_waitcnt lgkmcnt(7)
; DI void dn_prep_item(CParams& p, int layer, int it, int S, char* lds) {
;     ...
;       const float* Ah = Am + 4 * half;
; #pragma unroll
;       for (int i = 0; i < 64; ++i) {
;         float part = 0.f;
; #pragma unroll
;         for (int q = 0; q < (i + 7) / 8; ++q) {
;           const f32x4 a = *(const f32x4*)(Ah + i * 68 + 8 * q);
;           part += a[0] * xs[4 * q] + a[1] * xs[4 * q + 1] + a[2] * xs[4 * q + 2] + a[3] * xs[4 * q + 3];
;         }
;         const float other = __int_as_float(__builtin_amdgcn_update_dpp(0, __float_as_int(part), 0xB1, 0xf, 0xf, true));
;         const float xi = Rc[i * 64] - (part + other);
;         const int loc = ((i >> 3) << 2) + (i & 3);
;         if (((i >> 2) & 1) == 0) xs[loc] = (half == 0) ? xi : xs[loc];
;         else xs[loc] = (half == 1) ? xi : xs[loc];
;         if (i < 16 ? ((i & 7) == 7) : (i < 32 ? ((i & 3) == 3) : ((i & 1) == 1))) asm volatile("" ::: "memory");
;       }
;     }
	v_mul_f32_e32 v3, v201, v68
	v_fmac_f32_e32 v3, v200, v66
	v_fmac_f32_e32 v3, v202, v70
	v_fmac_f32_e32 v3, v203, v12
	v_add_f32_e32 v8, v2, v3
	ds_read2st64_b32 v[206:207], v42 offset0:14 offset1:15
	ds_read_b128 v[172:175], v43 offset:37120
	v_add_f32_dpp v8, v8, v8 quad_perm:[1, 0, 3, 2] row_mask:0xf bank_mask:0xf bound_ctrl:1
	s_waitcnt lgkmcnt(5)
	v_sub_f32_e32 v2, v204, v8
	v_cndmask_b32_e64 v8, v2, v13, s[46:47]
	v_mul_f32_e32 v2, v5, v177
	v_fmac_f32_e32 v2, v4, v176
	v_fmac_f32_e32 v2, v178, v6
	v_fmac_f32_e32 v2, v179, v7
	ds_read_b128 v[200:203], v43 offset:37152
	v_add_f32_e32 v2, 0, v2
	v_mul_f32_e32 v9, v180, v8
	v_fmac_f32_e32 v9, v181, v68
	v_fmac_f32_e32 v9, v182, v70
	v_fmac_f32_e32 v9, v183, v12
	ds_read_b128 v[176:179], v43 offset:37392
	v_add_f32_e32 v2, v2, v9
	s_nop 1
	v_add_f32_dpp v2, v2, v2 quad_perm:[1, 0, 3, 2] row_mask:0xf bank_mask:0xf bound_ctrl:1
	v_sub_f32_e32 v2, v205, v2
	v_cndmask_b32_e64 v9, v2, v67, s[46:47]
	v_mul_f32_e32 v2, v5, v185
	v_fmac_f32_e32 v2, v4, v184
	v_fmac_f32_e32 v2, v186, v6
	v_fmac_f32_e32 v2, v187, v7
	ds_read_b128 v[180:183], v43 offset:37424
	v_add_f32_e32 v2, 0, v2
	s_waitcnt lgkmcnt(7)
	v_mul_f32_e32 v3, v189, v9
	v_fmac_f32_e32 v3, v188, v8
	v_fmac_f32_e32 v3, v190, v70
	v_fmac_f32_e32 v3, v191, v12
	v_add_f32_e32 v10, v2, v3
	ds_read2st64_b32 v[208:209], v42 offset0:16 offset1:17
	ds_read_b128 v[184:187], v43 offset:37456
	v_add_f32_dpp v10, v10, v10 quad_perm:[1, 0, 3, 2] row_mask:0xf bank_mask:0xf bound_ctrl:1
	s_waitcnt lgkmcnt(6)
	v_sub_f32_e32 v2, v206, v10
	v_cndmask_b32_e64 v10, v2, v69, s[46:47]
	v_mul_f32_e32 v2, v5, v193
	v_fmac_f32_e32 v2, v4, v192
	v_fmac_f32_e32 v2, v6, v194
	v_fmac_f32_e32 v2, v195, v7
	ds_read_b128 v[188:191], v43 offset:37664
	v_add_f32_e32 v2, 0, v2
	v_mul_f32_e32 v13, v197, v9
	v_fmac_f32_e32 v13, v196, v8
	v_fmac_f32_e32 v13, v198, v10
	v_fmac_f32_e32 v13, v199, v12
	v_add_f32_e32 v2, v2, v13
	ds_read_b128 v[192:195], v43 offset:37696
	ds_read_b128 v[196:199], v43 offset:37728
	v_add_f32_dpp v2, v2, v2 quad_perm:[1, 0, 3, 2] row_mask:0xf bank_mask:0xf bound_ctrl:1
	v_sub_f32_e32 v2, v207, v2
	v_cndmask_b32_e64 v11, v2, v11, s[46:47]
	s_waitcnt lgkmcnt(8)
	v_mul_f32_e32 v2, v5, v173
	v_fmac_f32_e32 v2, v4, v172
	s_waitcnt lgkmcnt(7)
	v_mul_f32_e32 v3, v201, v9
	v_fmac_f32_e32 v2, v6, v174
	v_fmac_f32_e32 v3, v200, v8
	v_fmac_f32_e32 v2, v7, v175
	v_fmac_f32_e32 v3, v202, v10
	v_add_f32_e32 v2, 0, v2
	v_fmac_f32_e32 v3, v203, v11
	v_add_f32_e32 v12, v2, v3
	ds_read2st64_b32 v[204:205], v42 offset0:18 offset1:19
	ds_read_b128 v[172:175], v43 offset:37936
	v_add_f32_dpp v12, v12, v12 quad_perm:[1, 0, 3, 2] row_mask:0xf bank_mask:0xf bound_ctrl:1
	s_waitcnt lgkmcnt(6)
	v_sub_f32_e32 v12, v208, v12
	v_mul_f32_e32 v2, v5, v177
	v_fmac_f32_e32 v2, v4, v176
	v_fmac_f32_e32 v2, v6, v178
	v_fmac_f32_e32 v2, v7, v179
	ds_read_b128 v[200:203], v43 offset:37968
	v_cndmask_b32_e64 v16, 0, v12, s[46:47]
	v_add_f32_e32 v2, 0, v2
	v_mul_f32_e32 v13, v181, v9
	v_fmac_f32_e32 v13, v180, v8
	v_fmac_f32_e32 v13, v182, v10
	v_fmac_f32_e32 v13, v183, v11
	ds_read_b128 v[176:179], v43 offset:38000
	v_add_f32_e32 v2, v2, v13
	s_waitcnt lgkmcnt(7)
	v_mul_f32_e32 v13, v184, v16
	v_fmac_f32_e32 v13, 0, v185
	v_fmac_f32_e32 v13, 0, v186
	v_fmac_f32_e32 v13, 0, v187
	ds_read_b128 v[180:183], v43 offset:38208
	v_add_f32_e32 v2, v2, v13
	s_nop 1
	v_add_f32_dpp v2, v2, v2 quad_perm:[1, 0, 3, 2] row_mask:0xf bank_mask:0xf bound_ctrl:1
	v_sub_f32_e32 v13, v209, v2
	s_waitcnt lgkmcnt(7)
	v_mul_f32_e32 v2, v5, v189
	v_fmac_f32_e32 v2, v4, v188
	v_fmac_f32_e32 v2, v6, v190
	v_fmac_f32_e32 v2, v7, v191
	ds_read_b128 v[184:187], v43 offset:38240
	v_cndmask_b32_e64 v14, 0, v13, s[46:47]
	v_add_f32_e32 v2, 0, v2
	s_waitcnt lgkmcnt(7)
	v_mul_f32_e32 v3, v193, v9
	v_fmac_f32_e32 v3, v192, v8
	v_fmac_f32_e32 v3, v194, v10
	v_fmac_f32_e32 v3, v195, v11
	ds_read_b128 v[188:191], v43 offset:38272
	v_add_f32_e32 v2, v2, v3
	s_waitcnt lgkmcnt(7)
	v_mul_f32_e32 v3, v197, v14
	v_fmac_f32_e32 v3, v196, v16
	v_fmac_f32_e32 v3, 0, v198
	v_fmac_f32_e32 v3, 0, v199
	v_add_f32_e32 v15, v2, v3
	ds_read2st64_b32 v[206:207], v42 offset0:20 offset1:21
	ds_read_b128 v[192:195], v43 offset:38480
	v_add_f32_dpp v15, v15, v15 quad_perm:[1, 0, 3, 2] row_mask:0xf bank_mask:0xf bound_ctrl:1
	s_waitcnt lgkmcnt(8)
	v_sub_f32_e32 v2, v204, v15
	s_waitcnt lgkmcnt(7)
	v_mul_f32_e32 v15, v5, v173
	v_fmac_f32_e32 v15, v4, v172
	v_fmac_f32_e32 v15, v6, v174
	v_fmac_f32_e32 v15, v7, v175
	ds_read_b128 v[196:199], v43 offset:38512
	v_add_f32_e32 v15, 0, v15
	v_cndmask_b32_e64 v90, 0, v2, s[46:47]
	s_waitcnt lgkmcnt(7)
	v_mul_f32_e32 v17, v201, v9
	v_fmac_f32_e32 v17, v200, v8
	v_fmac_f32_e32 v17, v202, v10
	v_fmac_f32_e32 v17, v203, v11
	ds_read_b128 v[172:175], v43 offset:38544
	v_add_f32_e32 v15, v15, v17
	s_waitcnt lgkmcnt(7)
	v_mul_f32_e32 v17, v177, v14
	v_fmac_f32_e32 v17, v176, v16
	v_fmac_f32_e32 v17, v178, v90
	v_fmac_f32_e32 v17, 0, v179
	ds_read_b128 v[200:203], v43 offset:38752
	ds_read_b128 v[176:179], v43 offset:38784
	v_add_f32_e32 v15, v15, v17
	s_waitcnt lgkmcnt(8)
	v_mul_f32_e32 v17, v5, v181
	v_fmac_f32_e32 v17, v4, v180
	s_waitcnt lgkmcnt(7)
	v_mul_f32_e32 v66, v185, v9
	v_fmac_f32_e32 v17, v6, v182
	v_fmac_f32_e32 v66, v184, v8
	v_fmac_f32_e32 v17, v7, v183
	v_fmac_f32_e32 v66, v186, v10
	v_add_f32_e32 v17, 0, v17
	v_fmac_f32_e32 v66, v187, v11
	v_add_f32_e32 v17, v17, v66
	ds_read_b128 v[180:183], v43 offset:38816
	v_add_f32_dpp v15, v15, v15 quad_perm:[1, 0, 3, 2] row_mask:0xf bank_mask:0xf bound_ctrl:1
	v_sub_f32_e32 v3, v205, v15
	v_cndmask_b32_e64 v15, 0, v3, s[46:47]
	s_waitcnt lgkmcnt(7)
; DI void dn_prep_item(CParams& p, int layer, int it, int S, char* lds) {
;     ...
;       const float* Ah = Am + 4 * half;
; #pragma unroll
;       for (int i = 0; i < 64; ++i) {
;         float part = 0.f;
; #pragma unroll
;         for (int q = 0; q < (i + 7) / 8; ++q) {
;           const f32x4 a = *(const f32x4*)(Ah + i * 68 + 8 * q);
;           part += a[0] * xs[4 * q] + a[1] * xs[4 * q + 1] + a[2] * xs[4 * q + 2] + a[3] * xs[4 * q + 3];
;         }
;         const float other = __int_as_float(__builtin_amdgcn_update_dpp(0, __float_as_int(part), 0xB1, 0xf, 0xf, true));
;         const float xi = Rc[i * 64] - (part + other);
;         const int loc = ((i >> 3) << 2) + (i & 3);
;         if (((i >> 2) & 1) == 0) xs[loc] = (half == 0) ? xi : xs[loc];
;         else xs[loc] = (half == 1) ? xi : xs[loc];
;         if (i < 16 ? ((i & 7) == 7) : (i < 32 ? ((i & 3) == 3) : ((i & 1) == 1))) asm volatile("" ::: "memory");
;       }
;     }
	v_mul_f32_e32 v67, v189, v14
	v_fmac_f32_e32 v67, v188, v16
	v_fmac_f32_e32 v67, v190, v90
	v_fmac_f32_e32 v67, v191, v15
	v_add_f32_e32 v66, v17, v67
	ds_read2st64_b32 v[208:209], v42 offset0:22 offset1:23
	s_nop 0
	v_add_f32_dpp v66, v66, v66 quad_perm:[1, 0, 3, 2] row_mask:0xf bank_mask:0xf bound_ctrl:1
	s_waitcnt lgkmcnt(7)
	v_sub_f32_e32 v16, v206, v66
	ds_read_b128 v[184:187], v43 offset:39024
	v_cndmask_b32_e64 v12, v16, v12, s[46:47]
	s_waitcnt lgkmcnt(7)
	v_mul_f32_e32 v16, v5, v193
	v_fmac_f32_e32 v16, v4, v192
	v_fmac_f32_e32 v16, v6, v194
	v_fmac_f32_e32 v16, v7, v195
	ds_read_b128 v[188:191], v43 offset:39056
	v_add_f32_e32 v16, 0, v16
	s_waitcnt lgkmcnt(7)
	v_mul_f32_e32 v67, v197, v9
	v_fmac_f32_e32 v67, v196, v8
	v_fmac_f32_e32 v67, v198, v10
	v_fmac_f32_e32 v67, v199, v11
	v_add_f32_e32 v16, v16, v67
	ds_read_b128 v[192:195], v43 offset:39088
	s_waitcnt lgkmcnt(7)
	v_mul_f32_e32 v66, v172, v12
	v_fmac_f32_e32 v66, v173, v14
	v_fmac_f32_e32 v66, v174, v90
	v_fmac_f32_e32 v66, v175, v15
	v_add_f32_e32 v14, v16, v66
	ds_read_b128 v[196:199], v43 offset:39296
	s_nop 0
	v_add_f32_dpp v14, v14, v14 quad_perm:[1, 0, 3, 2] row_mask:0xf bank_mask:0xf bound_ctrl:1
	v_sub_f32_e32 v14, v207, v14
	v_cndmask_b32_e64 v13, v14, v13, s[46:47]
	s_waitcnt lgkmcnt(7)
	v_mul_f32_e32 v14, v5, v201
	v_fmac_f32_e32 v14, v4, v200
	v_fmac_f32_e32 v14, v6, v202
	v_fmac_f32_e32 v14, v7, v203
	ds_read_b128 v[172:175], v43 offset:39328
	v_add_f32_e32 v14, 0, v14
	s_waitcnt lgkmcnt(7)
	v_mul_f32_e32 v16, v177, v9
	v_fmac_f32_e32 v16, v176, v8
	v_fmac_f32_e32 v16, v178, v10
	v_fmac_f32_e32 v16, v179, v11
	ds_read_b128 v[200:203], v43 offset:40112
	v_add_f32_e32 v14, v14, v16
	s_waitcnt lgkmcnt(7)
	v_mul_f32_e32 v16, v181, v13
	v_fmac_f32_e32 v16, v180, v12
	v_fmac_f32_e32 v16, v182, v90
	v_fmac_f32_e32 v16, v183, v15
	v_add_f32_e32 v14, v14, v16
	ds_read2st64_b32 v[204:205], v42 offset0:24 offset1:25
	ds_read_b128 v[176:179], v43 offset:39360
	v_add_f32_dpp v14, v14, v14 quad_perm:[1, 0, 3, 2] row_mask:0xf bank_mask:0xf bound_ctrl:1
	s_waitcnt lgkmcnt(8)
	v_sub_f32_e32 v14, v208, v14
	v_cndmask_b32_e64 v14, v14, v2, s[46:47]
	s_waitcnt lgkmcnt(7)
	v_mul_f32_e32 v2, v5, v185
	v_fmac_f32_e32 v2, v4, v184
	v_fmac_f32_e32 v2, v6, v186
	v_fmac_f32_e32 v2, v7, v187
	ds_read_b128 v[180:183], v43 offset:39568
	v_add_f32_e32 v2, 0, v2
	s_waitcnt lgkmcnt(7)
	v_mul_f32_e32 v16, v189, v9
	v_fmac_f32_e32 v16, v8, v188
	v_fmac_f32_e32 v16, v190, v10
	v_fmac_f32_e32 v16, v191, v11
	ds_read_b128 v[184:187], v43 offset:39600
	v_add_f32_e32 v2, v2, v16
	s_waitcnt lgkmcnt(7)
	v_mul_f32_e32 v16, v193, v13
	v_fmac_f32_e32 v16, v192, v12
	v_fmac_f32_e32 v16, v194, v14
	v_fmac_f32_e32 v16, v195, v15
	ds_read_b128 v[188:191], v43 offset:39632
	ds_read_b128 v[192:195], v43 offset:39664
	v_add_f32_e32 v2, v2, v16
	s_nop 0
	s_nop 0
	v_add_f32_dpp v2, v2, v2 quad_perm:[1, 0, 3, 2] row_mask:0xf bank_mask:0xf bound_ctrl:1
	v_sub_f32_e32 v2, v209, v2
	v_cndmask_b32_e64 v15, v2, v3, s[46:47]
	s_waitcnt lgkmcnt(8)
	v_mul_f32_e32 v2, v5, v197
	v_fmac_f32_e32 v2, v4, v196
	v_fmac_f32_e32 v2, v6, v198
	v_fmac_f32_e32 v2, v7, v199
	ds_read_b128 v[196:199], v43 offset:39840
	s_waitcnt lgkmcnt(8)
	v_mul_f32_e32 v3, v173, v9
	v_fmac_f32_e32 v3, v8, v172
	v_fmac_f32_e32 v3, v174, v10
	v_add_f32_e32 v2, 0, v2
	v_fmac_f32_e32 v3, v175, v11
	ds_read_b128 v[172:175], v43 offset:39872
	v_add_f32_e32 v2, v2, v3
	s_waitcnt lgkmcnt(6)
	v_mul_f32_e32 v3, v177, v13
	v_fmac_f32_e32 v3, v176, v12
	v_fmac_f32_e32 v3, v178, v14
	v_fmac_f32_e32 v3, v179, v15
	v_add_f32_e32 v16, v2, v3
	ds_read2st64_b32 v[206:207], v42 offset0:26 offset1:27
	ds_read_b128 v[176:179], v43 offset:39904
	v_add_f32_dpp v16, v16, v16 quad_perm:[1, 0, 3, 2] row_mask:0xf bank_mask:0xf bound_ctrl:1
	v_sub_f32_e32 v16, v204, v16
	s_waitcnt lgkmcnt(7)
	v_mul_f32_e32 v2, v5, v181
	v_fmac_f32_e32 v2, v4, v180
	v_fmac_f32_e32 v2, v6, v182
	v_fmac_f32_e32 v2, v7, v183
	ds_read_b128 v[180:183], v43 offset:39936
	v_add_f32_e32 v2, 0, v2
	v_cndmask_b32_e64 v17, 0, v16, s[46:47]
	s_waitcnt lgkmcnt(7)
	v_mul_f32_e32 v67, v9, v185
	v_fmac_f32_e32 v67, v8, v184
	v_fmac_f32_e32 v67, v186, v10
	v_fmac_f32_e32 v67, v187, v11
	v_add_f32_e32 v2, v2, v67
	ds_read_b128 v[184:187], v43 offset:40144
	s_waitcnt lgkmcnt(7)
	v_mul_f32_e32 v67, v189, v13
	v_fmac_f32_e32 v67, v188, v12
	v_fmac_f32_e32 v67, v190, v14
	v_fmac_f32_e32 v67, v191, v15
	v_add_f32_e32 v2, v2, v67
	ds_read_b128 v[188:191], v43 offset:40176
	s_waitcnt lgkmcnt(7)
	v_mul_f32_e32 v66, v192, v17
	v_fmac_f32_e32 v66, 0, v193
	v_fmac_f32_e32 v66, 0, v194
	v_fmac_f32_e32 v66, 0, v195
	ds_read_b128 v[192:195], v43 offset:40208
	v_add_f32_e32 v2, v2, v66
	s_nop 1
	v_add_f32_dpp v2, v2, v2 quad_perm:[1, 0, 3, 2] row_mask:0xf bank_mask:0xf bound_ctrl:1
	v_sub_f32_e32 v66, v205, v2
	s_waitcnt lgkmcnt(7)
	v_mul_f32_e32 v2, v5, v197
	v_fmac_f32_e32 v2, v4, v196
	v_fmac_f32_e32 v2, v6, v198
	v_fmac_f32_e32 v2, v7, v199
	ds_read_b128 v[196:199], v43 offset:40384
	v_add_f32_e32 v2, 0, v2
	v_cndmask_b32_e64 v67, 0, v66, s[46:47]
	s_waitcnt lgkmcnt(7)
	v_mul_f32_e32 v3, v9, v173
	v_fmac_f32_e32 v3, v8, v172
	v_fmac_f32_e32 v3, v10, v174
	v_fmac_f32_e32 v3, v175, v11
	ds_read_b128 v[172:175], v43 offset:40416
	v_add_f32_e32 v2, v2, v3
	s_waitcnt lgkmcnt(6)
	v_mul_f32_e32 v3, v177, v13
	v_fmac_f32_e32 v3, v176, v12
	v_fmac_f32_e32 v3, v178, v14
	v_fmac_f32_e32 v3, v179, v15
	ds_read_b128 v[176:179], v43 offset:40448
	v_add_f32_e32 v2, v2, v3
	s_waitcnt lgkmcnt(6)
; DI void dn_prep_item(CParams& p, int layer, int it, int S, char* lds) {
;     ...
;       const float* Ah = Am + 4 * half;
; #pragma unroll
;       for (int i = 0; i < 64; ++i) {
;         float part = 0.f;
; #pragma unroll
;         for (int q = 0; q < (i + 7) / 8; ++q) {
;           const f32x4 a = *(const f32x4*)(Ah + i * 68 + 8 * q);
;           part += a[0] * xs[4 * q] + a[1] * xs[4 * q + 1] + a[2] * xs[4 * q + 2] + a[3] * xs[4 * q + 3];
;         }
;         const float other = __int_as_float(__builtin_amdgcn_update_dpp(0, __float_as_int(part), 0xB1, 0xf, 0xf, true));
;         const float xi = Rc[i * 64] - (part + other);
;         const int loc = ((i >> 3) << 2) + (i & 3);
;         if (((i >> 2) & 1) == 0) xs[loc] = (half == 0) ? xi : xs[loc];
;         else xs[loc] = (half == 1) ? xi : xs[loc];
;         if (i < 16 ? ((i & 7) == 7) : (i < 32 ? ((i & 3) == 3) : ((i & 1) == 1))) asm volatile("" ::: "memory");
;       }
;     }
	v_mul_f32_e32 v3, v181, v67
	v_fmac_f32_e32 v3, v180, v17
	v_fmac_f32_e32 v3, 0, v182
	v_fmac_f32_e32 v3, 0, v183
	v_add_f32_e32 v68, v2, v3
	ds_read2st64_b32 v[208:209], v42 offset0:28 offset1:29
	s_nop 0
	v_add_f32_dpp v68, v68, v68 quad_perm:[1, 0, 3, 2] row_mask:0xf bank_mask:0xf bound_ctrl:1
	v_sub_f32_e32 v70, v206, v68
	v_mul_f32_e32 v68, v5, v201
	v_fmac_f32_e32 v68, v4, v200
	v_fmac_f32_e32 v68, v6, v202
	v_fmac_f32_e32 v68, v7, v203
	ds_read_b128 v[180:183], v43 offset:40480
	v_add_f32_e32 v68, 0, v68
	v_cndmask_b32_e64 v2, 0, v70, s[46:47]
	s_waitcnt lgkmcnt(7)
	v_mul_f32_e32 v69, v9, v185
	v_fmac_f32_e32 v69, v8, v184
	v_fmac_f32_e32 v69, v10, v186
	v_fmac_f32_e32 v69, v11, v187
	ds_read_b128 v[200:203], v43 offset:40656
	v_add_f32_e32 v68, v68, v69
	s_waitcnt lgkmcnt(7)
	v_mul_f32_e32 v69, v189, v13
	v_fmac_f32_e32 v69, v188, v12
	v_fmac_f32_e32 v69, v190, v14
	v_fmac_f32_e32 v69, v191, v15
	ds_read_b128 v[184:187], v43 offset:40688
	v_add_f32_e32 v68, v68, v69
	s_waitcnt lgkmcnt(7)
	v_mul_f32_e32 v69, v193, v67
	v_fmac_f32_e32 v69, v192, v17
	v_fmac_f32_e32 v69, v194, v2
	v_fmac_f32_e32 v69, 0, v195
	ds_read_b128 v[188:191], v43 offset:40720
	ds_read_b128 v[192:195], v43 offset:40752
	v_add_f32_e32 v68, v68, v69
	ds_read2st64_b32 v[204:205], v42 offset0:30 offset1:31
	s_waitcnt lgkmcnt(8)
	v_mul_f32_e32 v71, v9, v173
	v_add_f32_dpp v68, v68, v68 quad_perm:[1, 0, 3, 2] row_mask:0xf bank_mask:0xf bound_ctrl:1
	v_sub_f32_e32 v68, v207, v68
	v_mul_f32_e32 v3, v5, v197
	v_fmac_f32_e32 v3, v4, v196
	v_fmac_f32_e32 v3, v6, v198
	v_fmac_f32_e32 v3, v7, v199
	ds_read_b128 v[196:199], v43 offset:40928
	v_fmac_f32_e32 v71, v8, v172
	v_fmac_f32_e32 v71, v10, v174
	v_add_f32_e32 v3, 0, v3
	v_fmac_f32_e32 v71, v11, v175
	v_add_f32_e32 v3, v3, v71
	s_waitcnt lgkmcnt(8)
	v_mul_f32_e32 v71, v177, v13
	v_fmac_f32_e32 v71, v176, v12
	v_fmac_f32_e32 v71, v178, v14
	v_fmac_f32_e32 v71, v179, v15
	ds_read_b128 v[172:175], v43 offset:40960
	v_add_f32_e32 v3, v3, v71
	v_cndmask_b32_e64 v69, 0, v68, s[46:47]
	s_waitcnt lgkmcnt(7)
	v_mul_f32_e32 v71, v181, v67
	v_fmac_f32_e32 v71, v180, v17
	v_fmac_f32_e32 v71, v182, v2
	v_fmac_f32_e32 v71, v183, v69
	ds_read_b128 v[176:179], v43 offset:40992
	v_add_f32_e32 v3, v3, v71
	s_nop 1
	v_add_f32_dpp v3, v3, v3 quad_perm:[1, 0, 3, 2] row_mask:0xf bank_mask:0xf bound_ctrl:1
	v_sub_f32_e32 v3, v208, v3
	v_cndmask_b32_e64 v16, v3, v16, s[46:47]
	s_waitcnt lgkmcnt(7)
	v_mul_f32_e32 v3, v5, v201
	v_fmac_f32_e32 v3, v4, v200
	v_fmac_f32_e32 v3, v6, v202
	v_fmac_f32_e32 v3, v7, v203
	ds_read_b128 v[180:183], v43 offset:41024
	v_add_f32_e32 v3, 0, v3
	s_waitcnt lgkmcnt(7)
	v_mul_f32_e32 v17, v9, v185
	v_fmac_f32_e32 v17, v8, v184
	v_fmac_f32_e32 v17, v10, v186
	v_fmac_f32_e32 v17, v11, v187
	ds_read_b128 v[200:203], v43 offset:41200
	v_add_f32_e32 v3, v3, v17
	s_waitcnt lgkmcnt(7)
	v_mul_f32_e32 v17, v189, v13
	v_fmac_f32_e32 v17, v188, v12
	v_fmac_f32_e32 v17, v190, v14
	v_fmac_f32_e32 v17, v191, v15
	ds_read_b128 v[184:187], v43 offset:41232
	v_add_f32_e32 v3, v3, v17
	s_waitcnt lgkmcnt(7)
	v_mul_f32_e32 v17, v192, v16
	v_fmac_f32_e32 v17, v193, v67
	v_fmac_f32_e32 v17, v194, v2
	v_fmac_f32_e32 v17, v195, v69
	ds_read_b128 v[188:191], v43 offset:41264
	v_add_f32_e32 v3, v3, v17
	s_nop 1
	v_add_f32_dpp v3, v3, v3 quad_perm:[1, 0, 3, 2] row_mask:0xf bank_mask:0xf bound_ctrl:1
	v_sub_f32_e32 v3, v209, v3
	v_cndmask_b32_e64 v17, v3, v66, s[46:47]
	s_waitcnt lgkmcnt(6)
	v_mul_f32_e32 v3, v5, v197
	v_fmac_f32_e32 v3, v4, v196
	v_fmac_f32_e32 v3, v6, v198
	v_fmac_f32_e32 v3, v7, v199
	ds_read_b128 v[192:195], v43 offset:41296
	v_add_f32_e32 v3, 0, v3
	s_waitcnt lgkmcnt(6)
	v_mul_f32_e32 v66, v9, v173
	v_fmac_f32_e32 v66, v8, v172
	v_fmac_f32_e32 v66, v10, v174
	v_fmac_f32_e32 v66, v11, v175
	ds_read_b128 v[196:199], v43 offset:41472
	v_add_f32_e32 v3, v3, v66
	s_waitcnt lgkmcnt(6)
	v_mul_f32_e32 v66, v177, v13
	v_fmac_f32_e32 v66, v176, v12
	v_fmac_f32_e32 v66, v178, v14
	v_fmac_f32_e32 v66, v179, v15
	ds_read_b128 v[172:175], v43 offset:41504
	v_add_f32_e32 v3, v3, v66
	s_waitcnt lgkmcnt(6)
	v_mul_f32_e32 v66, v181, v17
	v_fmac_f32_e32 v66, v180, v16
	v_fmac_f32_e32 v66, v182, v2
	v_fmac_f32_e32 v66, v183, v69
	v_add_f32_e32 v66, v3, v66
	ds_read2st64_b32 v[206:207], v42 offset0:32 offset1:33
	s_nop 0
	v_add_f32_dpp v66, v66, v66 quad_perm:[1, 0, 3, 2] row_mask:0xf bank_mask:0xf bound_ctrl:1
	v_sub_f32_e32 v2, v204, v66
	v_cndmask_b32_e64 v66, v2, v70, s[46:47]
	ds_read_b128 v[176:179], v43 offset:41536
	s_waitcnt lgkmcnt(7)
	v_mul_f32_e32 v2, v5, v201
	v_fmac_f32_e32 v2, v4, v200
	v_fmac_f32_e32 v2, v6, v202
	v_fmac_f32_e32 v2, v7, v203
	ds_read_b128 v[180:183], v43 offset:41568
	v_add_f32_e32 v2, 0, v2
	s_waitcnt lgkmcnt(7)
	v_mul_f32_e32 v67, v9, v185
	v_fmac_f32_e32 v67, v8, v184
	v_fmac_f32_e32 v67, v10, v186
	v_fmac_f32_e32 v67, v11, v187
	ds_read_b128 v[200:203], v43 offset:41744
	v_add_f32_e32 v2, v2, v67
	s_waitcnt lgkmcnt(7)
	v_mul_f32_e32 v67, v189, v13
	v_fmac_f32_e32 v67, v188, v12
	v_fmac_f32_e32 v67, v190, v14
	v_fmac_f32_e32 v67, v191, v15
	ds_read_b128 v[184:187], v43 offset:41776
	v_add_f32_e32 v2, v2, v67
	s_waitcnt lgkmcnt(7)
	v_mul_f32_e32 v67, v193, v17
	v_fmac_f32_e32 v67, v192, v16
	v_fmac_f32_e32 v67, v194, v66
	v_fmac_f32_e32 v67, v195, v69
	v_add_f32_e32 v2, v2, v67
	s_nop 1
	v_add_f32_dpp v2, v2, v2 quad_perm:[1, 0, 3, 2] row_mask:0xf bank_mask:0xf bound_ctrl:1
	v_sub_f32_e32 v2, v205, v2
	v_cndmask_b32_e64 v67, v2, v68, s[46:47]
	ds_read_b128 v[188:191], v43 offset:41808
	ds_read_b128 v[192:195], v43 offset:41840
	s_waitcnt lgkmcnt(8)
; DI void dn_prep_item(CParams& p, int layer, int it, int S, char* lds) {
;     ...
;       const float* Ah = Am + 4 * half;
; #pragma unroll
;       for (int i = 0; i < 64; ++i) {
;         float part = 0.f;
; #pragma unroll
;         for (int q = 0; q < (i + 7) / 8; ++q) {
;           const f32x4 a = *(const f32x4*)(Ah + i * 68 + 8 * q);
;           part += a[0] * xs[4 * q] + a[1] * xs[4 * q + 1] + a[2] * xs[4 * q + 2] + a[3] * xs[4 * q + 3];
;         }
;         const float other = __int_as_float(__builtin_amdgcn_update_dpp(0, __float_as_int(part), 0xB1, 0xf, 0xf, true));
;         const float xi = Rc[i * 64] - (part + other);
;         const int loc = ((i >> 3) << 2) + (i & 3);
;         if (((i >> 2) & 1) == 0) xs[loc] = (half == 0) ? xi : xs[loc];
;         else xs[loc] = (half == 1) ? xi : xs[loc];
;         if (i < 16 ? ((i & 7) == 7) : (i < 32 ? ((i & 3) == 3) : ((i & 1) == 1))) asm volatile("" ::: "memory");
;       }
;     }
	v_mul_f32_e32 v2, v5, v197
	v_fmac_f32_e32 v2, v4, v196
	v_fmac_f32_e32 v2, v6, v198
	v_fmac_f32_e32 v2, v7, v199
	ds_read_b128 v[196:199], v43 offset:41872
	s_waitcnt lgkmcnt(8)
	v_mul_f32_e32 v3, v9, v173
	v_fmac_f32_e32 v3, v8, v172
	v_fmac_f32_e32 v3, v10, v174
	v_add_f32_e32 v2, 0, v2
	v_fmac_f32_e32 v3, v11, v175
	v_add_f32_e32 v2, v2, v3
	s_waitcnt lgkmcnt(6)
	v_mul_f32_e32 v3, v177, v13
	v_fmac_f32_e32 v3, v176, v12
	v_fmac_f32_e32 v3, v178, v14
	v_fmac_f32_e32 v3, v179, v15
	ds_read_b128 v[172:175], v43 offset:42016
	v_add_f32_e32 v2, v2, v3
	s_waitcnt lgkmcnt(6)
	v_mul_f32_e32 v3, v181, v17
	v_fmac_f32_e32 v3, v180, v16
	v_fmac_f32_e32 v3, v182, v66
	v_fmac_f32_e32 v3, v183, v67
	v_add_f32_e32 v68, v2, v3
	ds_read2st64_b32 v[208:209], v42 offset0:34 offset1:35
	ds_read_b128 v[176:179], v43 offset:42048
	v_add_f32_dpp v68, v68, v68 quad_perm:[1, 0, 3, 2] row_mask:0xf bank_mask:0xf bound_ctrl:1
	v_sub_f32_e32 v68, v206, v68
	s_waitcnt lgkmcnt(7)
	v_mul_f32_e32 v2, v5, v201
	v_fmac_f32_e32 v2, v4, v200
	v_fmac_f32_e32 v2, v6, v202
	v_fmac_f32_e32 v2, v7, v203
	ds_read_b128 v[180:183], v43 offset:42080
	v_add_f32_e32 v2, 0, v2
	v_cndmask_b32_e64 v91, 0, v68, s[46:47]
	s_waitcnt lgkmcnt(7)
	v_mul_f32_e32 v69, v9, v185
	v_fmac_f32_e32 v69, v8, v184
	v_fmac_f32_e32 v69, v10, v186
	v_fmac_f32_e32 v69, v11, v187
	ds_read_b128 v[200:203], v43 offset:42288
	v_add_f32_e32 v2, v2, v69
	s_waitcnt lgkmcnt(7)
	v_mul_f32_e32 v69, v189, v13
	v_fmac_f32_e32 v69, v12, v188
	v_fmac_f32_e32 v69, v190, v14
	v_fmac_f32_e32 v69, v191, v15
	ds_read_b128 v[184:187], v43 offset:42112
	v_add_f32_e32 v2, v2, v69
	s_waitcnt lgkmcnt(7)
	v_mul_f32_e32 v69, v193, v17
	v_fmac_f32_e32 v69, v192, v16
	v_fmac_f32_e32 v69, v194, v66
	v_fmac_f32_e32 v69, v195, v67
	ds_read_b128 v[188:191], v43 offset:42144
	v_add_f32_e32 v2, v2, v69
	s_waitcnt lgkmcnt(7)
	v_mul_f32_e32 v69, v196, v91
	v_fmac_f32_e32 v69, 0, v197
	v_fmac_f32_e32 v69, 0, v198
	v_fmac_f32_e32 v69, 0, v199
	ds_read_b128 v[192:195], v43 offset:42320
	ds_read_b128 v[196:199], v43 offset:42352
	v_add_f32_e32 v2, v2, v69
	s_nop 1
	v_add_f32_dpp v2, v2, v2 quad_perm:[1, 0, 3, 2] row_mask:0xf bank_mask:0xf bound_ctrl:1
	v_sub_f32_e32 v69, v207, v2
	s_waitcnt lgkmcnt(8)
	v_mul_f32_e32 v2, v5, v173
	v_fmac_f32_e32 v2, v4, v172
	v_fmac_f32_e32 v2, v6, v174
	v_fmac_f32_e32 v2, v7, v175
	ds_read_b128 v[172:175], v43 offset:42384
	s_waitcnt lgkmcnt(7)
	v_mul_f32_e32 v3, v9, v177
	v_fmac_f32_e32 v3, v8, v176
	v_fmac_f32_e32 v3, v10, v178
	v_add_f32_e32 v2, 0, v2
	v_fmac_f32_e32 v3, v11, v179
	v_add_f32_e32 v2, v2, v3
	ds_read_b128 v[176:179], v43 offset:42416
	s_waitcnt lgkmcnt(7)
	v_mul_f32_e32 v3, v13, v181
	v_fmac_f32_e32 v3, v12, v180
	v_fmac_f32_e32 v3, v182, v14
	v_fmac_f32_e32 v3, v183, v15
	ds_read_b128 v[180:183], v43 offset:42560
	v_add_f32_e32 v2, v2, v3
	v_cndmask_b32_e64 v90, 0, v69, s[46:47]
	s_waitcnt lgkmcnt(6)
	v_mul_f32_e32 v3, v185, v17
	v_fmac_f32_e32 v3, v184, v16
	v_fmac_f32_e32 v3, v186, v66
	v_fmac_f32_e32 v3, v187, v67
	ds_read_b128 v[184:187], v43 offset:42592
	v_add_f32_e32 v2, v2, v3
	s_waitcnt lgkmcnt(6)
	v_mul_f32_e32 v3, v189, v90
	v_fmac_f32_e32 v3, v188, v91
	v_fmac_f32_e32 v3, 0, v190
	v_fmac_f32_e32 v3, 0, v191
	v_add_f32_e32 v70, v2, v3
	ds_read2st64_b32 v[204:205], v42 offset0:36 offset1:37
	s_nop 0
	v_add_f32_dpp v70, v70, v70 quad_perm:[1, 0, 3, 2] row_mask:0xf bank_mask:0xf bound_ctrl:1
	v_sub_f32_e32 v70, v208, v70
	v_mul_f32_e32 v2, v5, v201
	v_fmac_f32_e32 v2, v4, v200
	v_fmac_f32_e32 v2, v6, v202
	v_fmac_f32_e32 v2, v7, v203
	ds_read_b128 v[188:191], v43 offset:42624
	v_add_f32_e32 v2, 0, v2
	v_cndmask_b32_e64 v73, 0, v70, s[46:47]
	s_waitcnt lgkmcnt(7)
	v_mul_f32_e32 v71, v9, v193
	v_fmac_f32_e32 v71, v8, v192
	v_fmac_f32_e32 v71, v10, v194
	v_fmac_f32_e32 v71, v11, v195
	ds_read_b128 v[200:203], v43 offset:42656
	v_add_f32_e32 v2, v2, v71
	s_waitcnt lgkmcnt(7)
	v_mul_f32_e32 v71, v13, v197
	v_fmac_f32_e32 v71, v12, v196
	v_fmac_f32_e32 v71, v14, v198
	v_fmac_f32_e32 v71, v199, v15
	ds_read_b128 v[192:195], v43 offset:42688
	v_add_f32_e32 v2, v2, v71
	s_waitcnt lgkmcnt(7)
	v_mul_f32_e32 v71, v173, v17
	v_fmac_f32_e32 v71, v172, v16
	v_fmac_f32_e32 v71, v174, v66
	v_fmac_f32_e32 v71, v175, v67
	ds_read_b128 v[196:199], v43 offset:42832
	v_add_f32_e32 v2, v2, v71
	s_waitcnt lgkmcnt(7)
	v_mul_f32_e32 v71, v177, v90
	v_fmac_f32_e32 v71, v176, v91
	v_fmac_f32_e32 v71, v178, v73
	v_fmac_f32_e32 v71, 0, v179
	ds_read_b128 v[172:175], v43 offset:42864
	ds_read_b128 v[176:179], v43 offset:42896
	v_add_f32_e32 v2, v2, v71
	s_nop 1
	v_add_f32_dpp v2, v2, v2 quad_perm:[1, 0, 3, 2] row_mask:0xf bank_mask:0xf bound_ctrl:1
	v_sub_f32_e32 v71, v209, v2
	s_waitcnt lgkmcnt(8)
	v_mul_f32_e32 v2, v5, v181
	v_fmac_f32_e32 v2, v4, v180
	v_fmac_f32_e32 v2, v6, v182
	v_fmac_f32_e32 v2, v7, v183
	ds_read_b128 v[180:183], v43 offset:42928
	s_waitcnt lgkmcnt(8)
	v_mul_f32_e32 v3, v9, v185
	v_fmac_f32_e32 v3, v8, v184
	v_fmac_f32_e32 v3, v10, v186
	v_add_f32_e32 v2, 0, v2
	v_fmac_f32_e32 v3, v11, v187
	v_add_f32_e32 v2, v2, v3
	s_waitcnt lgkmcnt(6)
	v_mul_f32_e32 v3, v13, v189
	v_fmac_f32_e32 v3, v12, v188
	v_fmac_f32_e32 v3, v14, v190
	v_fmac_f32_e32 v3, v15, v191
	ds_read_b128 v[184:187], v43 offset:42960
	v_add_f32_e32 v2, v2, v3
	v_cndmask_b32_e64 v72, 0, v71, s[46:47]
	s_waitcnt lgkmcnt(6)
	v_mul_f32_e32 v3, v201, v17
	v_fmac_f32_e32 v3, v200, v16
	v_fmac_f32_e32 v3, v202, v66
	v_fmac_f32_e32 v3, v203, v67
	ds_read_b128 v[188:191], v43 offset:43104
	v_add_f32_e32 v2, v2, v3
	s_waitcnt lgkmcnt(6)
; DI void dn_prep_item(CParams& p, int layer, int it, int S, char* lds) {
;     ...
;     const int c = tid >> 1, half = tid & 1;
;     {
;       const float* Rc = (c < 64) ? (RU + c) : (RW + (c - 64));
;       const float* Ah = Am + 4 * half;
; #pragma unroll
;       for (int i = 0; i < 64; ++i) {
;         float part = 0.f;
; #pragma unroll
;         for (int q = 0; q < (i + 7) / 8; ++q) {
;           const f32x4 a = *(const f32x4*)(Ah + i * 68 + 8 * q);
;           part += a[0] * xs[4 * q] + a[1] * xs[4 * q + 1] + a[2] * xs[4 * q + 2] + a[3] * xs[4 * q + 3];
;         }
;         const float other = __int_as_float(__builtin_amdgcn_update_dpp(0, __float_as_int(part), 0xB1, 0xf, 0xf, true));
;         const float xi = Rc[i * 64] - (part + other);
;         const int loc = ((i >> 3) << 2) + (i & 3);
;         if (((i >> 2) & 1) == 0) xs[loc] = (half == 0) ? xi : xs[loc];
;         else xs[loc] = (half == 1) ? xi : xs[loc];
;         if (i < 16 ? ((i & 7) == 7) : (i < 32 ? ((i & 3) == 3) : ((i & 1) == 1))) asm volatile("" ::: "memory");
;       }
;     }
	v_mul_f32_e32 v3, v193, v90
	v_fmac_f32_e32 v3, v192, v91
	v_fmac_f32_e32 v3, v194, v73
	v_fmac_f32_e32 v3, v195, v72
	v_add_f32_e32 v91, v2, v3
	ds_read2st64_b32 v[206:207], v42 offset0:38 offset1:39
	ds_read_b128 v[200:203], v43 offset:43136
	v_add_f32_dpp v91, v91, v91 quad_perm:[1, 0, 3, 2] row_mask:0xf bank_mask:0xf bound_ctrl:1
	v_sub_f32_e32 v2, v204, v91
	v_cndmask_b32_e64 v68, v2, v68, s[46:47]
	s_waitcnt lgkmcnt(7)
	v_mul_f32_e32 v2, v5, v197
	v_fmac_f32_e32 v2, v4, v196
	v_fmac_f32_e32 v2, v6, v198
	v_fmac_f32_e32 v2, v7, v199
	ds_read_b128 v[192:195], v43 offset:43168
	v_add_f32_e32 v2, 0, v2
	s_waitcnt lgkmcnt(7)
	v_mul_f32_e32 v91, v9, v173
	v_fmac_f32_e32 v91, v8, v172
	v_fmac_f32_e32 v91, v10, v174
	v_fmac_f32_e32 v91, v11, v175
	ds_read_b128 v[196:199], v43 offset:43200
	v_add_f32_e32 v2, v2, v91
	s_waitcnt lgkmcnt(7)
	v_mul_f32_e32 v91, v13, v177
	v_fmac_f32_e32 v91, v12, v176
	v_fmac_f32_e32 v91, v14, v178
	v_fmac_f32_e32 v91, v15, v179
	ds_read_b128 v[172:175], v43 offset:43232
	v_add_f32_e32 v2, v2, v91
	s_waitcnt lgkmcnt(7)
	v_mul_f32_e32 v91, v181, v17
	v_fmac_f32_e32 v91, v180, v16
	v_fmac_f32_e32 v91, v182, v66
	v_fmac_f32_e32 v91, v183, v67
	ds_read_b128 v[176:179], v43 offset:43376
	v_add_f32_e32 v2, v2, v91
	s_waitcnt lgkmcnt(7)
	v_mul_f32_e32 v91, v184, v68
	v_fmac_f32_e32 v91, v185, v90
	v_fmac_f32_e32 v91, v186, v73
	v_fmac_f32_e32 v91, v187, v72
	v_add_f32_e32 v2, v2, v91
	ds_read_b128 v[180:183], v43 offset:43408
	ds_read_b128 v[184:187], v43 offset:43440
	v_add_f32_dpp v2, v2, v2 quad_perm:[1, 0, 3, 2] row_mask:0xf bank_mask:0xf bound_ctrl:1
	v_sub_f32_e32 v2, v205, v2
	v_cndmask_b32_e64 v69, v2, v69, s[46:47]
	s_waitcnt lgkmcnt(8)
	v_mul_f32_e32 v2, v5, v189
	v_fmac_f32_e32 v2, v4, v188
	v_fmac_f32_e32 v2, v6, v190
	v_fmac_f32_e32 v2, v7, v191
	ds_read_b128 v[188:191], v43 offset:43472
	s_waitcnt lgkmcnt(7)
	v_mul_f32_e32 v3, v9, v201
	v_fmac_f32_e32 v3, v8, v200
	v_fmac_f32_e32 v3, v10, v202
	v_add_f32_e32 v2, 0, v2
	v_fmac_f32_e32 v3, v11, v203
	v_add_f32_e32 v2, v2, v3
	s_waitcnt lgkmcnt(6)
	v_mul_f32_e32 v3, v13, v193
	v_fmac_f32_e32 v3, v12, v192
	v_fmac_f32_e32 v3, v14, v194
	v_fmac_f32_e32 v3, v15, v195
	ds_read_b128 v[200:203], v43 offset:43504
	v_add_f32_e32 v2, v2, v3
	s_waitcnt lgkmcnt(6)
	v_mul_f32_e32 v3, v197, v17
	v_fmac_f32_e32 v3, v196, v16
	v_fmac_f32_e32 v3, v198, v66
	v_fmac_f32_e32 v3, v199, v67
	ds_read_b128 v[192:195], v43 offset:43648
	v_add_f32_e32 v2, v2, v3
	s_waitcnt lgkmcnt(6)
	v_mul_f32_e32 v3, v173, v69
	v_fmac_f32_e32 v3, v172, v68
	v_fmac_f32_e32 v3, v174, v73
	v_fmac_f32_e32 v3, v175, v72
	v_add_f32_e32 v73, v2, v3
	ds_read2st64_b32 v[208:209], v42 offset0:40 offset1:41
	ds_read_b128 v[196:199], v43 offset:43680
	v_add_f32_dpp v73, v73, v73 quad_perm:[1, 0, 3, 2] row_mask:0xf bank_mask:0xf bound_ctrl:1
	v_sub_f32_e32 v2, v206, v73
	v_cndmask_b32_e64 v70, v2, v70, s[46:47]
	s_waitcnt lgkmcnt(7)
	v_mul_f32_e32 v2, v5, v177
	v_fmac_f32_e32 v2, v4, v176
	v_fmac_f32_e32 v2, v6, v178
	v_fmac_f32_e32 v2, v7, v179
	ds_read_b128 v[172:175], v43 offset:43712
	v_add_f32_e32 v2, 0, v2
	s_waitcnt lgkmcnt(7)
	v_mul_f32_e32 v73, v9, v181
	v_fmac_f32_e32 v73, v8, v180
	v_fmac_f32_e32 v73, v10, v182
	v_fmac_f32_e32 v73, v11, v183
	ds_read_b128 v[176:179], v43 offset:43744
	v_add_f32_e32 v2, v2, v73
	s_waitcnt lgkmcnt(7)
	v_mul_f32_e32 v73, v13, v185
	v_fmac_f32_e32 v73, v12, v184
	v_fmac_f32_e32 v73, v14, v186
	v_fmac_f32_e32 v73, v15, v187
	ds_read_b128 v[180:183], v43 offset:43776
	v_add_f32_e32 v2, v2, v73
	s_waitcnt lgkmcnt(7)
	v_mul_f32_e32 v73, v189, v17
	v_fmac_f32_e32 v73, v188, v16
	v_fmac_f32_e32 v73, v190, v66
	v_fmac_f32_e32 v73, v191, v67
	ds_read_b128 v[184:187], v43 offset:43920
	v_add_f32_e32 v2, v2, v73
	s_waitcnt lgkmcnt(7)
	v_mul_f32_e32 v73, v201, v69
	v_fmac_f32_e32 v73, v200, v68
	v_fmac_f32_e32 v73, v202, v70
	v_fmac_f32_e32 v73, v203, v72
	ds_read_b128 v[188:191], v43 offset:43952
	ds_read_b128 v[200:203], v43 offset:43984
	v_add_f32_e32 v2, v2, v73
	s_nop 1
	v_add_f32_dpp v2, v2, v2 quad_perm:[1, 0, 3, 2] row_mask:0xf bank_mask:0xf bound_ctrl:1
	v_sub_f32_e32 v2, v207, v2
	v_cndmask_b32_e64 v71, v2, v71, s[46:47]
	s_waitcnt lgkmcnt(8)
	v_mul_f32_e32 v2, v5, v193
	v_fmac_f32_e32 v2, v4, v192
	v_fmac_f32_e32 v2, v6, v194
	v_fmac_f32_e32 v2, v7, v195
	ds_read_b128 v[192:195], v43 offset:44016
	s_waitcnt lgkmcnt(7)
	v_mul_f32_e32 v3, v9, v197
	v_fmac_f32_e32 v3, v8, v196
	v_fmac_f32_e32 v3, v10, v198
	v_add_f32_e32 v2, 0, v2
	v_fmac_f32_e32 v3, v11, v199
	v_add_f32_e32 v2, v2, v3
	s_waitcnt lgkmcnt(6)
	v_mul_f32_e32 v3, v13, v173
	v_fmac_f32_e32 v3, v12, v172
	v_fmac_f32_e32 v3, v14, v174
	v_fmac_f32_e32 v3, v15, v175
	ds_read_b128 v[196:199], v43 offset:44048
	v_add_f32_e32 v2, v2, v3
	s_waitcnt lgkmcnt(6)
	v_mul_f32_e32 v3, v177, v17
	v_fmac_f32_e32 v3, v16, v176
	v_fmac_f32_e32 v3, v178, v66
	v_fmac_f32_e32 v3, v179, v67
	ds_read_b128 v[172:175], v43 offset:44080
	v_add_f32_e32 v2, v2, v3
	s_waitcnt lgkmcnt(6)
	v_mul_f32_e32 v3, v181, v69
	v_fmac_f32_e32 v3, v180, v68
	v_fmac_f32_e32 v3, v182, v70
	v_fmac_f32_e32 v3, v183, v71
	v_add_f32_e32 v72, v2, v3
	ds_read2st64_b32 v[204:205], v42 offset0:42 offset1:43
	ds_read_b128 v[176:179], v43 offset:44192
	v_add_f32_dpp v72, v72, v72 quad_perm:[1, 0, 3, 2] row_mask:0xf bank_mask:0xf bound_ctrl:1
	v_sub_f32_e32 v72, v208, v72
	s_waitcnt lgkmcnt(7)
	v_mul_f32_e32 v2, v5, v185
	v_fmac_f32_e32 v2, v4, v184
	v_fmac_f32_e32 v2, v6, v186
	v_fmac_f32_e32 v2, v7, v187
	ds_read_b128 v[180:183], v43 offset:44224
	v_add_f32_e32 v2, 0, v2
	v_cndmask_b32_e64 v73, 0, v72, s[46:47]
	s_waitcnt lgkmcnt(7)
; DI void dn_prep_item(CParams& p, int layer, int it, int S, char* lds) {
;     ...
;     const int c = tid >> 1, half = tid & 1;
;     {
;       const float* Rc = (c < 64) ? (RU + c) : (RW + (c - 64));
;       const float* Ah = Am + 4 * half;
; #pragma unroll
;       for (int i = 0; i < 64; ++i) {
;         float part = 0.f;
; #pragma unroll
;         for (int q = 0; q < (i + 7) / 8; ++q) {
;           const f32x4 a = *(const f32x4*)(Ah + i * 68 + 8 * q);
;           part += a[0] * xs[4 * q] + a[1] * xs[4 * q + 1] + a[2] * xs[4 * q + 2] + a[3] * xs[4 * q + 3];
;         }
;         const float other = __int_as_float(__builtin_amdgcn_update_dpp(0, __float_as_int(part), 0xB1, 0xf, 0xf, true));
;         const float xi = Rc[i * 64] - (part + other);
;         const int loc = ((i >> 3) << 2) + (i & 3);
;         if (((i >> 2) & 1) == 0) xs[loc] = (half == 0) ? xi : xs[loc];
;         else xs[loc] = (half == 1) ? xi : xs[loc];
;         if (i < 16 ? ((i & 7) == 7) : (i < 32 ? ((i & 3) == 3) : ((i & 1) == 1))) asm volatile("" ::: "memory");
;       }
;     }
	v_mul_f32_e32 v91, v9, v189
	v_fmac_f32_e32 v91, v8, v188
	v_fmac_f32_e32 v91, v10, v190
	v_fmac_f32_e32 v91, v11, v191
	v_add_f32_e32 v2, v2, v91
	ds_read_b128 v[184:187], v43 offset:44256
	s_waitcnt lgkmcnt(7)
	v_mul_f32_e32 v91, v13, v201
	v_fmac_f32_e32 v91, v12, v200
	v_fmac_f32_e32 v91, v14, v202
	v_fmac_f32_e32 v91, v15, v203
	v_add_f32_e32 v2, v2, v91
	ds_read_b128 v[188:191], v43 offset:44288
	s_waitcnt lgkmcnt(7)
	v_mul_f32_e32 v91, v17, v193
	v_fmac_f32_e32 v91, v16, v192
	v_fmac_f32_e32 v91, v194, v66
	v_fmac_f32_e32 v91, v195, v67
	v_add_f32_e32 v2, v2, v91
	ds_read_b128 v[200:203], v43 offset:44320
	s_waitcnt lgkmcnt(7)
	v_mul_f32_e32 v91, v197, v69
	v_fmac_f32_e32 v91, v196, v68
	v_fmac_f32_e32 v91, v198, v70
	v_fmac_f32_e32 v91, v199, v71
	v_add_f32_e32 v2, v2, v91
	ds_read_b128 v[192:195], v43 offset:44352
	ds_read_b128 v[196:199], v43 offset:44464
	s_waitcnt lgkmcnt(8)
	v_mul_f32_e32 v90, v172, v73
	v_fmac_f32_e32 v90, 0, v173
	v_fmac_f32_e32 v90, 0, v174
	v_fmac_f32_e32 v90, 0, v175
	ds_read_b128 v[172:175], v43 offset:44496
	v_add_f32_e32 v2, v2, v90
	s_nop 1
	v_add_f32_dpp v2, v2, v2 quad_perm:[1, 0, 3, 2] row_mask:0xf bank_mask:0xf bound_ctrl:1
	v_sub_f32_e32 v90, v209, v2
	s_waitcnt lgkmcnt(7)
	v_mul_f32_e32 v2, v5, v177
	v_fmac_f32_e32 v2, v4, v176
	v_fmac_f32_e32 v2, v6, v178
	v_fmac_f32_e32 v2, v7, v179
	ds_read_b128 v[176:179], v43 offset:44528
	s_waitcnt lgkmcnt(7)
	v_mul_f32_e32 v3, v9, v181
	v_fmac_f32_e32 v3, v8, v180
	v_fmac_f32_e32 v3, v10, v182
	v_add_f32_e32 v2, 0, v2
	v_fmac_f32_e32 v3, v11, v183
	v_add_f32_e32 v2, v2, v3
	s_waitcnt lgkmcnt(6)
	v_mul_f32_e32 v3, v13, v185
	v_fmac_f32_e32 v3, v12, v184
	v_fmac_f32_e32 v3, v14, v186
	v_fmac_f32_e32 v3, v15, v187
	ds_read_b128 v[180:183], v43 offset:44560
	v_add_f32_e32 v2, v2, v3
	v_cndmask_b32_e64 v94, 0, v90, s[46:47]
	s_waitcnt lgkmcnt(6)
	v_mul_f32_e32 v3, v17, v189
	v_fmac_f32_e32 v3, v16, v188
	v_fmac_f32_e32 v3, v66, v190
	v_fmac_f32_e32 v3, v191, v67
	ds_read_b128 v[184:187], v43 offset:44592
	v_add_f32_e32 v2, v2, v3
	s_waitcnt lgkmcnt(6)
	v_mul_f32_e32 v3, v201, v69
	v_fmac_f32_e32 v3, v200, v68
	v_fmac_f32_e32 v3, v202, v70
	v_fmac_f32_e32 v3, v203, v71
	ds_read_b128 v[188:191], v43 offset:44624
	v_add_f32_e32 v2, v2, v3
	s_waitcnt lgkmcnt(6)
	v_mul_f32_e32 v3, v193, v94
	v_fmac_f32_e32 v3, v192, v73
	v_fmac_f32_e32 v3, 0, v194
	v_fmac_f32_e32 v3, 0, v195
	v_add_f32_e32 v91, v2, v3
	ds_read2st64_b32 v[206:207], v42 offset0:44 offset1:45
	ds_read_b128 v[200:203], v43 offset:44736
	v_add_f32_dpp v91, v91, v91 quad_perm:[1, 0, 3, 2] row_mask:0xf bank_mask:0xf bound_ctrl:1
	v_sub_f32_e32 v91, v204, v91
	s_waitcnt lgkmcnt(7)
	v_mul_f32_e32 v2, v5, v197
	v_fmac_f32_e32 v2, v4, v196
	v_fmac_f32_e32 v2, v6, v198
	v_fmac_f32_e32 v2, v7, v199
	ds_read_b128 v[192:195], v43 offset:44768
	v_add_f32_e32 v2, 0, v2
	v_cndmask_b32_e64 v95, 0, v91, s[46:47]
	s_waitcnt lgkmcnt(7)
	v_mul_f32_e32 v92, v9, v173
	v_fmac_f32_e32 v92, v8, v172
	v_fmac_f32_e32 v92, v10, v174
	v_fmac_f32_e32 v92, v11, v175
	ds_read_b128 v[196:199], v43 offset:44800
	v_add_f32_e32 v2, v2, v92
	s_waitcnt lgkmcnt(7)
	v_mul_f32_e32 v92, v13, v177
	v_fmac_f32_e32 v92, v12, v176
	v_fmac_f32_e32 v92, v14, v178
	v_fmac_f32_e32 v92, v15, v179
	ds_read_b128 v[172:175], v43 offset:44832
	v_add_f32_e32 v2, v2, v92
	s_waitcnt lgkmcnt(7)
	v_mul_f32_e32 v92, v17, v181
	v_fmac_f32_e32 v92, v16, v180
	v_fmac_f32_e32 v92, v66, v182
	v_fmac_f32_e32 v92, v67, v183
	ds_read_b128 v[176:179], v43 offset:44864
	v_add_f32_e32 v2, v2, v92
	s_waitcnt lgkmcnt(7)
	v_mul_f32_e32 v92, v185, v69
	v_fmac_f32_e32 v92, v184, v68
	v_fmac_f32_e32 v92, v186, v70
	v_fmac_f32_e32 v92, v187, v71
	ds_read_b128 v[180:183], v43 offset:44896
	v_add_f32_e32 v2, v2, v92
	s_waitcnt lgkmcnt(7)
	v_mul_f32_e32 v92, v189, v94
	v_fmac_f32_e32 v92, v188, v73
	v_fmac_f32_e32 v92, v190, v95
	v_fmac_f32_e32 v92, 0, v191
	ds_read_b128 v[184:187], v43 offset:45008
	ds_read_b128 v[188:191], v43 offset:45040
	v_add_f32_e32 v2, v2, v92
	s_nop 1
	v_add_f32_dpp v2, v2, v2 quad_perm:[1, 0, 3, 2] row_mask:0xf bank_mask:0xf bound_ctrl:1
	v_sub_f32_e32 v92, v205, v2
	s_waitcnt lgkmcnt(7)
	v_mul_f32_e32 v2, v5, v201
	v_fmac_f32_e32 v2, v4, v200
	v_fmac_f32_e32 v2, v6, v202
	v_fmac_f32_e32 v2, v7, v203
	ds_read_b128 v[200:203], v43 offset:45072
	s_waitcnt lgkmcnt(7)
	v_mul_f32_e32 v3, v9, v193
	v_fmac_f32_e32 v3, v8, v192
	v_fmac_f32_e32 v3, v10, v194
	v_add_f32_e32 v2, 0, v2
	v_fmac_f32_e32 v3, v11, v195
	v_add_f32_e32 v2, v2, v3
	s_waitcnt lgkmcnt(6)
	v_mul_f32_e32 v3, v13, v197
	v_fmac_f32_e32 v3, v12, v196
	v_fmac_f32_e32 v3, v14, v198
	v_fmac_f32_e32 v3, v15, v199
	ds_read_b128 v[192:195], v43 offset:45104
	v_add_f32_e32 v2, v2, v3
	v_cndmask_b32_e64 v93, 0, v92, s[46:47]
	s_waitcnt lgkmcnt(6)
	v_mul_f32_e32 v3, v17, v173
	v_fmac_f32_e32 v3, v16, v172
	v_fmac_f32_e32 v3, v66, v174
	v_fmac_f32_e32 v3, v67, v175
	ds_read_b128 v[196:199], v43 offset:45136
	v_add_f32_e32 v2, v2, v3
	s_waitcnt lgkmcnt(6)
	v_mul_f32_e32 v3, v177, v69
	v_fmac_f32_e32 v3, v176, v68
	v_fmac_f32_e32 v3, v178, v70
	v_fmac_f32_e32 v3, v179, v71
	ds_read_b128 v[172:175], v43 offset:45168
	v_add_f32_e32 v2, v2, v3
	s_waitcnt lgkmcnt(6)
	v_mul_f32_e32 v3, v181, v94
	v_fmac_f32_e32 v3, v180, v73
	v_fmac_f32_e32 v3, v182, v95
	v_fmac_f32_e32 v3, v183, v93
	v_add_f32_e32 v73, v2, v3
	ds_read2st64_b32 v[208:209], v42 offset0:46 offset1:47
	ds_read_b128 v[176:179], v43 offset:45280
	v_add_f32_dpp v73, v73, v73 quad_perm:[1, 0, 3, 2] row_mask:0xf bank_mask:0xf bound_ctrl:1
	v_sub_f32_e32 v2, v206, v73
	v_cndmask_b32_e64 v72, v2, v72, s[46:47]
	s_waitcnt lgkmcnt(7)
; DI void dn_prep_item(CParams& p, int layer, int it, int S, char* lds) {
;     ...
;     const int c = tid >> 1, half = tid & 1;
;     {
;       const float* Rc = (c < 64) ? (RU + c) : (RW + (c - 64));
;       const float* Ah = Am + 4 * half;
; #pragma unroll
;       for (int i = 0; i < 64; ++i) {
;         float part = 0.f;
; #pragma unroll
;         for (int q = 0; q < (i + 7) / 8; ++q) {
;           const f32x4 a = *(const f32x4*)(Ah + i * 68 + 8 * q);
;           part += a[0] * xs[4 * q] + a[1] * xs[4 * q + 1] + a[2] * xs[4 * q + 2] + a[3] * xs[4 * q + 3];
;         }
;         const float other = __int_as_float(__builtin_amdgcn_update_dpp(0, __float_as_int(part), 0xB1, 0xf, 0xf, true));
;         const float xi = Rc[i * 64] - (part + other);
;         const int loc = ((i >> 3) << 2) + (i & 3);
;         if (((i >> 2) & 1) == 0) xs[loc] = (half == 0) ? xi : xs[loc];
;         else xs[loc] = (half == 1) ? xi : xs[loc];
;         if (i < 16 ? ((i & 7) == 7) : (i < 32 ? ((i & 3) == 3) : ((i & 1) == 1))) asm volatile("" ::: "memory");
;       }
;     }
	v_mul_f32_e32 v2, v5, v185
	v_fmac_f32_e32 v2, v4, v184
	v_fmac_f32_e32 v2, v6, v186
	v_fmac_f32_e32 v2, v7, v187
	ds_read_b128 v[180:183], v43 offset:45312
	v_add_f32_e32 v2, 0, v2
	s_waitcnt lgkmcnt(7)
	v_mul_f32_e32 v73, v9, v189
	v_fmac_f32_e32 v73, v8, v188
	v_fmac_f32_e32 v73, v10, v190
	v_fmac_f32_e32 v73, v11, v191
	ds_read_b128 v[184:187], v43 offset:45344
	v_add_f32_e32 v2, v2, v73
	s_waitcnt lgkmcnt(7)
	v_mul_f32_e32 v73, v13, v201
	v_fmac_f32_e32 v73, v12, v200
	v_fmac_f32_e32 v73, v14, v202
	v_fmac_f32_e32 v73, v15, v203
	ds_read_b128 v[188:191], v43 offset:45376
	v_add_f32_e32 v2, v2, v73
	s_waitcnt lgkmcnt(7)
	v_mul_f32_e32 v73, v17, v193
	v_fmac_f32_e32 v73, v16, v192
	v_fmac_f32_e32 v73, v66, v194
	v_fmac_f32_e32 v73, v67, v195
	ds_read_b128 v[200:203], v43 offset:45408
	v_add_f32_e32 v2, v2, v73
	s_waitcnt lgkmcnt(7)
	v_mul_f32_e32 v73, v197, v69
	v_fmac_f32_e32 v73, v196, v68
	v_fmac_f32_e32 v73, v198, v70
	v_fmac_f32_e32 v73, v199, v71
	ds_read_b128 v[192:195], v43 offset:45440
	v_add_f32_e32 v2, v2, v73
	s_waitcnt lgkmcnt(7)
	v_mul_f32_e32 v73, v172, v72
	v_fmac_f32_e32 v73, v173, v94
	v_fmac_f32_e32 v73, v174, v95
	v_fmac_f32_e32 v73, v175, v93
	ds_read_b128 v[196:199], v43 offset:45552
	ds_read_b128 v[172:175], v43 offset:45584
	v_add_f32_e32 v2, v2, v73
	s_nop 1
	v_add_f32_dpp v2, v2, v2 quad_perm:[1, 0, 3, 2] row_mask:0xf bank_mask:0xf bound_ctrl:1
	v_sub_f32_e32 v2, v207, v2
	v_cndmask_b32_e64 v73, v2, v90, s[46:47]
	s_waitcnt lgkmcnt(7)
	v_mul_f32_e32 v2, v5, v177
	v_fmac_f32_e32 v2, v4, v176
	v_fmac_f32_e32 v2, v6, v178
	v_fmac_f32_e32 v2, v7, v179
	ds_read_b128 v[176:179], v43 offset:45616
	s_waitcnt lgkmcnt(7)
	v_mul_f32_e32 v3, v9, v181
	v_fmac_f32_e32 v3, v8, v180
	v_fmac_f32_e32 v3, v10, v182
	v_add_f32_e32 v2, 0, v2
	v_fmac_f32_e32 v3, v11, v183
	v_add_f32_e32 v2, v2, v3
	s_waitcnt lgkmcnt(6)
	v_mul_f32_e32 v3, v13, v185
	v_fmac_f32_e32 v3, v12, v184
	v_fmac_f32_e32 v3, v14, v186
	v_fmac_f32_e32 v3, v15, v187
	ds_read_b128 v[180:183], v43 offset:45648
	v_add_f32_e32 v2, v2, v3
	s_waitcnt lgkmcnt(6)
	v_mul_f32_e32 v3, v17, v189
	v_fmac_f32_e32 v3, v16, v188
	v_fmac_f32_e32 v3, v66, v190
	v_fmac_f32_e32 v3, v67, v191
	ds_read_b128 v[184:187], v43 offset:45680
	v_add_f32_e32 v2, v2, v3
	s_waitcnt lgkmcnt(6)
	v_mul_f32_e32 v3, v201, v69
	v_fmac_f32_e32 v3, v200, v68
	v_fmac_f32_e32 v3, v202, v70
	v_fmac_f32_e32 v3, v203, v71
	ds_read_b128 v[188:191], v43 offset:45712
	v_add_f32_e32 v2, v2, v3
	s_waitcnt lgkmcnt(6)
	v_mul_f32_e32 v3, v193, v73
	v_fmac_f32_e32 v3, v192, v72
	v_fmac_f32_e32 v3, v194, v95
	v_fmac_f32_e32 v3, v195, v93
	v_add_f32_e32 v90, v2, v3
	ds_read2st64_b32 v[204:205], v42 offset0:48 offset1:49
	ds_read_b128 v[200:203], v43 offset:45824
	v_add_f32_dpp v90, v90, v90 quad_perm:[1, 0, 3, 2] row_mask:0xf bank_mask:0xf bound_ctrl:1
	v_sub_f32_e32 v2, v208, v90
	v_cndmask_b32_e64 v90, v2, v91, s[46:47]
	s_waitcnt lgkmcnt(7)
	v_mul_f32_e32 v2, v5, v197
	v_fmac_f32_e32 v2, v4, v196
	v_fmac_f32_e32 v2, v6, v198
	v_fmac_f32_e32 v2, v7, v199
	ds_read_b128 v[192:195], v43 offset:45856
	v_add_f32_e32 v2, 0, v2
	s_waitcnt lgkmcnt(7)
	v_mul_f32_e32 v91, v9, v173
	v_fmac_f32_e32 v91, v8, v172
	v_fmac_f32_e32 v91, v10, v174
	v_fmac_f32_e32 v91, v11, v175
	ds_read_b128 v[196:199], v43 offset:45888
	v_add_f32_e32 v2, v2, v91
	s_waitcnt lgkmcnt(7)
	v_mul_f32_e32 v91, v13, v177
	v_fmac_f32_e32 v91, v12, v176
	v_fmac_f32_e32 v91, v14, v178
	v_fmac_f32_e32 v91, v15, v179
	ds_read_b128 v[172:175], v43 offset:45920
	v_add_f32_e32 v2, v2, v91
	s_waitcnt lgkmcnt(7)
	v_mul_f32_e32 v91, v17, v181
	v_fmac_f32_e32 v91, v16, v180
	v_fmac_f32_e32 v91, v66, v182
	v_fmac_f32_e32 v91, v67, v183
	ds_read_b128 v[176:179], v43 offset:45952
	v_add_f32_e32 v2, v2, v91
	s_waitcnt lgkmcnt(7)
	v_mul_f32_e32 v91, v185, v69
	v_fmac_f32_e32 v91, v68, v184
	v_fmac_f32_e32 v91, v186, v70
	v_fmac_f32_e32 v91, v187, v71
	ds_read_b128 v[180:183], v43 offset:45984
	v_add_f32_e32 v2, v2, v91
	s_waitcnt lgkmcnt(7)
	v_mul_f32_e32 v91, v189, v73
	v_fmac_f32_e32 v91, v188, v72
	v_fmac_f32_e32 v91, v190, v90
	v_fmac_f32_e32 v91, v191, v93
	v_add_f32_e32 v2, v2, v91
	s_nop 1
	v_add_f32_dpp v2, v2, v2 quad_perm:[1, 0, 3, 2] row_mask:0xf bank_mask:0xf bound_ctrl:1
	v_sub_f32_e32 v2, v209, v2
	v_cndmask_b32_e64 v91, v2, v92, s[46:47]
	ds_read_b128 v[184:187], v43 offset:46096
	ds_read_b128 v[188:191], v43 offset:46128
	s_waitcnt lgkmcnt(7)
	v_mul_f32_e32 v2, v5, v201
	v_fmac_f32_e32 v2, v4, v200
	v_fmac_f32_e32 v2, v6, v202
	v_fmac_f32_e32 v2, v7, v203
	ds_read_b128 v[200:203], v43 offset:46160
	s_waitcnt lgkmcnt(7)
	v_mul_f32_e32 v3, v9, v193
	v_fmac_f32_e32 v3, v8, v192
	v_fmac_f32_e32 v3, v10, v194
	v_add_f32_e32 v2, 0, v2
	v_fmac_f32_e32 v3, v11, v195
	v_add_f32_e32 v2, v2, v3
	s_waitcnt lgkmcnt(6)
	v_mul_f32_e32 v3, v13, v197
	v_fmac_f32_e32 v3, v12, v196
	v_fmac_f32_e32 v3, v14, v198
	v_fmac_f32_e32 v3, v15, v199
	ds_read_b128 v[192:195], v43 offset:46192
	v_add_f32_e32 v2, v2, v3
	s_waitcnt lgkmcnt(6)
	v_mul_f32_e32 v3, v17, v173
	v_fmac_f32_e32 v3, v16, v172
	v_fmac_f32_e32 v3, v66, v174
	v_fmac_f32_e32 v3, v67, v175
	ds_read_b128 v[196:199], v43 offset:46224
	v_add_f32_e32 v2, v2, v3
	s_waitcnt lgkmcnt(6)
	v_mul_f32_e32 v3, v69, v177
	v_fmac_f32_e32 v3, v68, v176
	v_fmac_f32_e32 v3, v178, v70
	v_fmac_f32_e32 v3, v179, v71
	ds_read_b128 v[172:175], v43 offset:46256
	v_add_f32_e32 v2, v2, v3
	s_waitcnt lgkmcnt(6)
	v_mul_f32_e32 v3, v181, v73
	v_fmac_f32_e32 v3, v180, v72
	v_fmac_f32_e32 v3, v182, v90
	v_fmac_f32_e32 v3, v183, v91
	v_add_f32_e32 v92, v2, v3
	ds_read2st64_b32 v[206:207], v42 offset0:50 offset1:51
	ds_read_b128 v[176:179], v43 offset:46288
	v_add_f32_dpp v92, v92, v92 quad_perm:[1, 0, 3, 2] row_mask:0xf bank_mask:0xf bound_ctrl:1
	v_sub_f32_e32 v92, v204, v92
	s_waitcnt lgkmcnt(7)
; DI void dn_prep_item(CParams& p, int layer, int it, int S, char* lds) {
;     ...
;     const int c = tid >> 1, half = tid & 1;
;     {
;       const float* Rc = (c < 64) ? (RU + c) : (RW + (c - 64));
;       const float* Ah = Am + 4 * half;
; #pragma unroll
;       for (int i = 0; i < 64; ++i) {
;         float part = 0.f;
; #pragma unroll
;         for (int q = 0; q < (i + 7) / 8; ++q) {
;           const f32x4 a = *(const f32x4*)(Ah + i * 68 + 8 * q);
;           part += a[0] * xs[4 * q] + a[1] * xs[4 * q + 1] + a[2] * xs[4 * q + 2] + a[3] * xs[4 * q + 3];
;         }
;         const float other = __int_as_float(__builtin_amdgcn_update_dpp(0, __float_as_int(part), 0xB1, 0xf, 0xf, true));
;         const float xi = Rc[i * 64] - (part + other);
;         const int loc = ((i >> 3) << 2) + (i & 3);
;         if (((i >> 2) & 1) == 0) xs[loc] = (half == 0) ? xi : xs[loc];
;         else xs[loc] = (half == 1) ? xi : xs[loc];
;         if (i < 16 ? ((i & 7) == 7) : (i < 32 ? ((i & 3) == 3) : ((i & 1) == 1))) asm volatile("" ::: "memory");
;       }
;     }
	v_mul_f32_e32 v2, v5, v185
	v_fmac_f32_e32 v2, v4, v184
	v_fmac_f32_e32 v2, v6, v186
	v_fmac_f32_e32 v2, v7, v187
	ds_read_b128 v[180:183], v43 offset:46368
	v_add_f32_e32 v2, 0, v2
	v_cndmask_b32_e64 v99, 0, v92, s[46:47]
	s_waitcnt lgkmcnt(7)
	v_mul_f32_e32 v93, v9, v189
	v_fmac_f32_e32 v93, v8, v188
	v_fmac_f32_e32 v93, v10, v190
	v_fmac_f32_e32 v93, v11, v191
	ds_read_b128 v[184:187], v43 offset:46400
	v_add_f32_e32 v2, v2, v93
	s_waitcnt lgkmcnt(7)
	v_mul_f32_e32 v93, v13, v201
	v_fmac_f32_e32 v93, v12, v200
	v_fmac_f32_e32 v93, v14, v202
	v_fmac_f32_e32 v93, v15, v203
	ds_read_b128 v[188:191], v43 offset:46432
	v_add_f32_e32 v2, v2, v93
	s_waitcnt lgkmcnt(7)
	v_mul_f32_e32 v93, v17, v193
	v_fmac_f32_e32 v93, v16, v192
	v_fmac_f32_e32 v93, v66, v194
	v_fmac_f32_e32 v93, v67, v195
	ds_read_b128 v[200:203], v43 offset:46640
	v_add_f32_e32 v2, v2, v93
	s_waitcnt lgkmcnt(7)
	v_mul_f32_e32 v93, v69, v197
	v_fmac_f32_e32 v93, v68, v196
	v_fmac_f32_e32 v93, v70, v198
	v_fmac_f32_e32 v93, v199, v71
	ds_read_b128 v[192:195], v43 offset:46464
	v_add_f32_e32 v2, v2, v93
	s_waitcnt lgkmcnt(7)
	v_mul_f32_e32 v93, v173, v73
	v_fmac_f32_e32 v93, v172, v72
	v_fmac_f32_e32 v93, v174, v90
	v_fmac_f32_e32 v93, v175, v91
	ds_read_b128 v[196:199], v43 offset:46496
	v_add_f32_e32 v2, v2, v93
	s_waitcnt lgkmcnt(6)
	v_mul_f32_e32 v93, v176, v99
	v_fmac_f32_e32 v93, 0, v177
	v_fmac_f32_e32 v93, 0, v178
	v_fmac_f32_e32 v93, 0, v179
	ds_read_b128 v[172:175], v43 offset:46528
	ds_read_b128 v[176:179], v43 offset:46560
	v_add_f32_e32 v2, v2, v93
	s_nop 1
	v_add_f32_dpp v2, v2, v2 quad_perm:[1, 0, 3, 2] row_mask:0xf bank_mask:0xf bound_ctrl:1
	v_sub_f32_e32 v93, v205, v2
	s_waitcnt lgkmcnt(7)
	v_mul_f32_e32 v2, v5, v181
	v_fmac_f32_e32 v2, v4, v180
	v_fmac_f32_e32 v2, v6, v182
	v_fmac_f32_e32 v2, v7, v183
	ds_read_b128 v[180:183], v43 offset:46672
	s_waitcnt lgkmcnt(7)
	v_mul_f32_e32 v3, v9, v185
	v_fmac_f32_e32 v3, v8, v184
	v_fmac_f32_e32 v3, v10, v186
	v_add_f32_e32 v2, 0, v2
	v_fmac_f32_e32 v3, v11, v187
	v_add_f32_e32 v2, v2, v3
	ds_read_b128 v[184:187], v43 offset:46704
	s_waitcnt lgkmcnt(7)
	v_mul_f32_e32 v3, v13, v189
	v_fmac_f32_e32 v3, v12, v188
	v_fmac_f32_e32 v3, v14, v190
	v_fmac_f32_e32 v3, v15, v191
	ds_read_b128 v[188:191], v43 offset:46736
	v_add_f32_e32 v2, v2, v3
	v_cndmask_b32_e64 v98, 0, v93, s[46:47]
	s_waitcnt lgkmcnt(6)
	v_mul_f32_e32 v3, v17, v193
	v_fmac_f32_e32 v3, v16, v192
	v_fmac_f32_e32 v3, v66, v194
	v_fmac_f32_e32 v3, v67, v195
	ds_read_b128 v[192:195], v43 offset:46768
	v_add_f32_e32 v2, v2, v3
	s_waitcnt lgkmcnt(6)
	v_mul_f32_e32 v3, v69, v197
	v_fmac_f32_e32 v3, v68, v196
	v_fmac_f32_e32 v3, v70, v198
	v_fmac_f32_e32 v3, v71, v199
	ds_read_b128 v[196:199], v43 offset:46800
	v_add_f32_e32 v2, v2, v3
	s_waitcnt lgkmcnt(6)
	v_mul_f32_e32 v3, v173, v73
	v_fmac_f32_e32 v3, v172, v72
	v_fmac_f32_e32 v3, v174, v90
	v_fmac_f32_e32 v3, v175, v91
	ds_read_b128 v[172:175], v43 offset:46832
	v_add_f32_e32 v2, v2, v3
	s_waitcnt lgkmcnt(6)
	v_mul_f32_e32 v3, v177, v98
	v_fmac_f32_e32 v3, v176, v99
	v_fmac_f32_e32 v3, 0, v178
	v_fmac_f32_e32 v3, 0, v179
	v_add_f32_e32 v94, v2, v3
	ds_read2st64_b32 v[208:209], v42 offset0:52 offset1:53
	s_nop 0
	v_add_f32_dpp v94, v94, v94 quad_perm:[1, 0, 3, 2] row_mask:0xf bank_mask:0xf bound_ctrl:1
	v_sub_f32_e32 v94, v206, v94
	v_mul_f32_e32 v2, v5, v201
	v_fmac_f32_e32 v2, v4, v200
	v_fmac_f32_e32 v2, v6, v202
	v_fmac_f32_e32 v2, v7, v203
	ds_read_b128 v[176:179], v43 offset:46912
	v_add_f32_e32 v2, 0, v2
	v_cndmask_b32_e64 v97, 0, v94, s[46:47]
	s_waitcnt lgkmcnt(7)
	v_mul_f32_e32 v95, v9, v181
	v_fmac_f32_e32 v95, v8, v180
	v_fmac_f32_e32 v95, v10, v182
	v_fmac_f32_e32 v95, v11, v183
	ds_read_b128 v[200:203], v43 offset:46944
	v_add_f32_e32 v2, v2, v95
	s_waitcnt lgkmcnt(7)
	v_mul_f32_e32 v95, v13, v185
	v_fmac_f32_e32 v95, v12, v184
	v_fmac_f32_e32 v95, v14, v186
	v_fmac_f32_e32 v95, v15, v187
	ds_read_b128 v[180:183], v43 offset:46976
	v_add_f32_e32 v2, v2, v95
	s_waitcnt lgkmcnt(7)
	v_mul_f32_e32 v95, v17, v189
	v_fmac_f32_e32 v95, v16, v188
	v_fmac_f32_e32 v95, v66, v190
	v_fmac_f32_e32 v95, v67, v191
	ds_read_b128 v[184:187], v43 offset:47008
	v_add_f32_e32 v2, v2, v95
	s_waitcnt lgkmcnt(7)
	v_mul_f32_e32 v95, v69, v193
	v_fmac_f32_e32 v95, v68, v192
	v_fmac_f32_e32 v95, v70, v194
	v_fmac_f32_e32 v95, v71, v195
	ds_read_b128 v[188:191], v43 offset:47040
	v_add_f32_e32 v2, v2, v95
	s_waitcnt lgkmcnt(7)
	v_mul_f32_e32 v95, v197, v73
	v_fmac_f32_e32 v95, v196, v72
	v_fmac_f32_e32 v95, v198, v90
	v_fmac_f32_e32 v95, v199, v91
	ds_read_b128 v[192:195], v43 offset:47072
	v_add_f32_e32 v2, v2, v95
	s_waitcnt lgkmcnt(7)
	v_mul_f32_e32 v95, v173, v98
	v_fmac_f32_e32 v95, v172, v99
	v_fmac_f32_e32 v95, v174, v97
	v_fmac_f32_e32 v95, 0, v175
	ds_read_b128 v[196:199], v43 offset:47104
	ds_read_b128 v[172:175], v43 offset:47184
	v_add_f32_e32 v2, v2, v95
	s_nop 1
	v_add_f32_dpp v2, v2, v2 quad_perm:[1, 0, 3, 2] row_mask:0xf bank_mask:0xf bound_ctrl:1
	v_sub_f32_e32 v95, v207, v2
	s_waitcnt lgkmcnt(7)
	v_mul_f32_e32 v2, v5, v177
	v_fmac_f32_e32 v2, v4, v176
	v_fmac_f32_e32 v2, v6, v178
	v_fmac_f32_e32 v2, v7, v179
	ds_read_b128 v[176:179], v43 offset:47216
	s_waitcnt lgkmcnt(7)
	v_mul_f32_e32 v3, v9, v201
	v_fmac_f32_e32 v3, v8, v200
	v_fmac_f32_e32 v3, v10, v202
	v_add_f32_e32 v2, 0, v2
	v_fmac_f32_e32 v3, v11, v203
	v_add_f32_e32 v2, v2, v3
	s_waitcnt lgkmcnt(6)
	v_mul_f32_e32 v3, v13, v181
	v_fmac_f32_e32 v3, v12, v180
	v_fmac_f32_e32 v3, v14, v182
	v_fmac_f32_e32 v3, v15, v183
	ds_read_b128 v[200:203], v43 offset:47248
	v_add_f32_e32 v2, v2, v3
	v_cndmask_b32_e64 v96, 0, v95, s[46:47]
	s_waitcnt lgkmcnt(6)
; DI void dn_prep_item(CParams& p, int layer, int it, int S, char* lds) {
;     ...
;     const int c = tid >> 1, half = tid & 1;
;     {
;       const float* Rc = (c < 64) ? (RU + c) : (RW + (c - 64));
;       const float* Ah = Am + 4 * half;
; #pragma unroll
;       for (int i = 0; i < 64; ++i) {
;         float part = 0.f;
; #pragma unroll
;         for (int q = 0; q < (i + 7) / 8; ++q) {
;           const f32x4 a = *(const f32x4*)(Ah + i * 68 + 8 * q);
;           part += a[0] * xs[4 * q] + a[1] * xs[4 * q + 1] + a[2] * xs[4 * q + 2] + a[3] * xs[4 * q + 3];
;         }
;         const float other = __int_as_float(__builtin_amdgcn_update_dpp(0, __float_as_int(part), 0xB1, 0xf, 0xf, true));
;         const float xi = Rc[i * 64] - (part + other);
;         const int loc = ((i >> 3) << 2) + (i & 3);
;         if (((i >> 2) & 1) == 0) xs[loc] = (half == 0) ? xi : xs[loc];
;         else xs[loc] = (half == 1) ? xi : xs[loc];
;         if (i < 16 ? ((i & 7) == 7) : (i < 32 ? ((i & 3) == 3) : ((i & 1) == 1))) asm volatile("" ::: "memory");
;       }
;     }
	v_mul_f32_e32 v3, v17, v185
	v_fmac_f32_e32 v3, v16, v184
	v_fmac_f32_e32 v3, v66, v186
	v_fmac_f32_e32 v3, v67, v187
	ds_read_b128 v[180:183], v43 offset:47280
	v_add_f32_e32 v2, v2, v3
	s_waitcnt lgkmcnt(6)
	v_mul_f32_e32 v3, v69, v189
	v_fmac_f32_e32 v3, v68, v188
	v_fmac_f32_e32 v3, v70, v190
	v_fmac_f32_e32 v3, v71, v191
	ds_read_b128 v[184:187], v43 offset:47312
	v_add_f32_e32 v2, v2, v3
	s_waitcnt lgkmcnt(6)
	v_mul_f32_e32 v3, v193, v73
	v_fmac_f32_e32 v3, v192, v72
	v_fmac_f32_e32 v3, v194, v90
	v_fmac_f32_e32 v3, v195, v91
	ds_read_b128 v[188:191], v43 offset:47344
	v_add_f32_e32 v2, v2, v3
	s_waitcnt lgkmcnt(6)
	v_mul_f32_e32 v3, v197, v98
	v_fmac_f32_e32 v3, v196, v99
	v_fmac_f32_e32 v3, v198, v97
	v_fmac_f32_e32 v3, v199, v96
	v_add_f32_e32 v99, v2, v3
	ds_read2st64_b32 v[204:205], v42 offset0:54 offset1:55
	ds_read_b128 v[192:195], v43 offset:47376
	v_add_f32_dpp v99, v99, v99 quad_perm:[1, 0, 3, 2] row_mask:0xf bank_mask:0xf bound_ctrl:1
	v_sub_f32_e32 v2, v208, v99
	v_cndmask_b32_e64 v92, v2, v92, s[46:47]
	s_waitcnt lgkmcnt(7)
	v_mul_f32_e32 v2, v5, v173
	v_fmac_f32_e32 v2, v4, v172
	v_fmac_f32_e32 v2, v6, v174
	v_fmac_f32_e32 v2, v7, v175
	ds_read_b128 v[196:199], v43 offset:47456
	v_add_f32_e32 v2, 0, v2
	s_waitcnt lgkmcnt(7)
	v_mul_f32_e32 v99, v9, v177
	v_fmac_f32_e32 v99, v8, v176
	v_fmac_f32_e32 v99, v10, v178
	v_fmac_f32_e32 v99, v11, v179
	ds_read_b128 v[172:175], v43 offset:47488
	v_add_f32_e32 v2, v2, v99
	s_waitcnt lgkmcnt(7)
	v_mul_f32_e32 v99, v13, v201
	v_fmac_f32_e32 v99, v12, v200
	v_fmac_f32_e32 v99, v14, v202
	v_fmac_f32_e32 v99, v15, v203
	ds_read_b128 v[176:179], v43 offset:47520
	v_add_f32_e32 v2, v2, v99
	s_waitcnt lgkmcnt(7)
	v_mul_f32_e32 v99, v17, v181
	v_fmac_f32_e32 v99, v16, v180
	v_fmac_f32_e32 v99, v66, v182
	v_fmac_f32_e32 v99, v67, v183
	ds_read_b128 v[200:203], v43 offset:47552
	v_add_f32_e32 v2, v2, v99
	s_waitcnt lgkmcnt(7)
	v_mul_f32_e32 v99, v69, v185
	v_fmac_f32_e32 v99, v68, v184
	v_fmac_f32_e32 v99, v70, v186
	v_fmac_f32_e32 v99, v71, v187
	ds_read_b128 v[180:183], v43 offset:47584
	v_add_f32_e32 v2, v2, v99
	s_waitcnt lgkmcnt(7)
	v_mul_f32_e32 v99, v189, v73
	v_fmac_f32_e32 v99, v72, v188
	v_fmac_f32_e32 v99, v190, v90
	v_fmac_f32_e32 v99, v191, v91
	ds_read_b128 v[184:187], v43 offset:47616
	v_add_f32_e32 v2, v2, v99
	s_waitcnt lgkmcnt(6)
	v_mul_f32_e32 v99, v192, v92
	v_fmac_f32_e32 v99, v193, v98
	v_fmac_f32_e32 v99, v194, v97
	v_fmac_f32_e32 v99, v195, v96
	v_add_f32_e32 v2, v2, v99
	ds_read_b128 v[188:191], v43 offset:47648
	ds_read_b128 v[192:195], v43 offset:47728
	v_add_f32_dpp v2, v2, v2 quad_perm:[1, 0, 3, 2] row_mask:0xf bank_mask:0xf bound_ctrl:1
	v_sub_f32_e32 v2, v209, v2
	v_cndmask_b32_e64 v93, v2, v93, s[46:47]
	s_waitcnt lgkmcnt(7)
	v_mul_f32_e32 v2, v5, v197
	v_fmac_f32_e32 v2, v4, v196
	v_fmac_f32_e32 v2, v6, v198
	v_fmac_f32_e32 v2, v7, v199
	ds_read_b128 v[196:199], v43 offset:47760
	s_waitcnt lgkmcnt(7)
	v_mul_f32_e32 v3, v9, v173
	v_fmac_f32_e32 v3, v8, v172
	v_fmac_f32_e32 v3, v10, v174
	v_add_f32_e32 v2, 0, v2
	v_fmac_f32_e32 v3, v11, v175
	v_add_f32_e32 v2, v2, v3
	s_waitcnt lgkmcnt(6)
	v_mul_f32_e32 v3, v13, v177
	v_fmac_f32_e32 v3, v12, v176
	v_fmac_f32_e32 v3, v14, v178
	v_fmac_f32_e32 v3, v15, v179
	ds_read_b128 v[172:175], v43 offset:47792
	v_add_f32_e32 v2, v2, v3
	s_waitcnt lgkmcnt(6)
	v_mul_f32_e32 v3, v17, v201
	v_fmac_f32_e32 v3, v16, v200
	v_fmac_f32_e32 v3, v66, v202
	v_fmac_f32_e32 v3, v67, v203
	ds_read_b128 v[176:179], v43 offset:47824
	v_add_f32_e32 v2, v2, v3
	s_waitcnt lgkmcnt(6)
	v_mul_f32_e32 v3, v69, v181
	v_fmac_f32_e32 v3, v68, v180
	v_fmac_f32_e32 v3, v70, v182
	v_fmac_f32_e32 v3, v71, v183
	ds_read_b128 v[200:203], v43 offset:47856
	v_add_f32_e32 v2, v2, v3
	s_waitcnt lgkmcnt(6)
	v_mul_f32_e32 v3, v73, v185
	v_fmac_f32_e32 v3, v72, v184
	v_fmac_f32_e32 v3, v186, v90
	v_fmac_f32_e32 v3, v187, v91
	ds_read_b128 v[180:183], v43 offset:47888
	v_add_f32_e32 v2, v2, v3
	s_waitcnt lgkmcnt(6)
	v_mul_f32_e32 v3, v189, v93
	v_fmac_f32_e32 v3, v188, v92
	v_fmac_f32_e32 v3, v190, v97
	v_fmac_f32_e32 v3, v191, v96
	v_add_f32_e32 v97, v2, v3
	ds_read2st64_b32 v[206:207], v42 offset0:56 offset1:57
	ds_read_b128 v[184:187], v43 offset:47920
	v_add_f32_dpp v97, v97, v97 quad_perm:[1, 0, 3, 2] row_mask:0xf bank_mask:0xf bound_ctrl:1
	v_sub_f32_e32 v2, v204, v97
	v_cndmask_b32_e64 v94, v2, v94, s[46:47]
	s_waitcnt lgkmcnt(7)
	v_mul_f32_e32 v2, v5, v193
	v_fmac_f32_e32 v2, v4, v192
	v_fmac_f32_e32 v2, v6, v194
	v_fmac_f32_e32 v2, v7, v195
	ds_read_b128 v[188:191], v43 offset:48000
	v_add_f32_e32 v2, 0, v2
	s_waitcnt lgkmcnt(7)
	v_mul_f32_e32 v97, v9, v197
	v_fmac_f32_e32 v97, v8, v196
	v_fmac_f32_e32 v97, v10, v198
	v_fmac_f32_e32 v97, v11, v199
	ds_read_b128 v[192:195], v43 offset:48032
	v_add_f32_e32 v2, v2, v97
	s_waitcnt lgkmcnt(7)
	v_mul_f32_e32 v97, v13, v173
	v_fmac_f32_e32 v97, v12, v172
	v_fmac_f32_e32 v97, v14, v174
	v_fmac_f32_e32 v97, v15, v175
	ds_read_b128 v[196:199], v43 offset:48064
	v_add_f32_e32 v2, v2, v97
	s_waitcnt lgkmcnt(7)
	v_mul_f32_e32 v97, v17, v177
	v_fmac_f32_e32 v97, v16, v176
	v_fmac_f32_e32 v97, v66, v178
	v_fmac_f32_e32 v97, v67, v179
	ds_read_b128 v[172:175], v43 offset:48096
	v_add_f32_e32 v2, v2, v97
	s_waitcnt lgkmcnt(7)
	v_mul_f32_e32 v97, v69, v201
	v_fmac_f32_e32 v97, v68, v200
	v_fmac_f32_e32 v97, v70, v202
	v_fmac_f32_e32 v97, v71, v203
	ds_read_b128 v[176:179], v43 offset:48128
	v_add_f32_e32 v2, v2, v97
	s_waitcnt lgkmcnt(7)
	v_mul_f32_e32 v97, v73, v181
	v_fmac_f32_e32 v97, v72, v180
	v_fmac_f32_e32 v97, v90, v182
	v_fmac_f32_e32 v97, v183, v91
	ds_read_b128 v[200:203], v43 offset:48160
	v_add_f32_e32 v2, v2, v97
	s_waitcnt lgkmcnt(6)
; DI void dn_prep_item(CParams& p, int layer, int it, int S, char* lds) {
;     ...
;     const int c = tid >> 1, half = tid & 1;
;     {
;       const float* Rc = (c < 64) ? (RU + c) : (RW + (c - 64));
;       const float* Ah = Am + 4 * half;
; #pragma unroll
;       for (int i = 0; i < 64; ++i) {
;         float part = 0.f;
; #pragma unroll
;         for (int q = 0; q < (i + 7) / 8; ++q) {
;           const f32x4 a = *(const f32x4*)(Ah + i * 68 + 8 * q);
;           part += a[0] * xs[4 * q] + a[1] * xs[4 * q + 1] + a[2] * xs[4 * q + 2] + a[3] * xs[4 * q + 3];
;         }
;         const float other = __int_as_float(__builtin_amdgcn_update_dpp(0, __float_as_int(part), 0xB1, 0xf, 0xf, true));
;         const float xi = Rc[i * 64] - (part + other);
;         const int loc = ((i >> 3) << 2) + (i & 3);
;         if (((i >> 2) & 1) == 0) xs[loc] = (half == 0) ? xi : xs[loc];
;         else xs[loc] = (half == 1) ? xi : xs[loc];
;         if (i < 16 ? ((i & 7) == 7) : (i < 32 ? ((i & 3) == 3) : ((i & 1) == 1))) asm volatile("" ::: "memory");
;       }
;     }
	v_mul_f32_e32 v97, v185, v93
	v_fmac_f32_e32 v97, v184, v92
	v_fmac_f32_e32 v97, v186, v94
	v_fmac_f32_e32 v97, v187, v96
	v_add_f32_e32 v2, v2, v97
	ds_read_b128 v[180:183], v43 offset:48192
	ds_read_b128 v[184:187], v43 offset:48272
	v_add_f32_dpp v2, v2, v2 quad_perm:[1, 0, 3, 2] row_mask:0xf bank_mask:0xf bound_ctrl:1
	v_sub_f32_e32 v2, v205, v2
	v_cndmask_b32_e64 v95, v2, v95, s[46:47]
	s_waitcnt lgkmcnt(7)
	v_mul_f32_e32 v2, v5, v189
	v_fmac_f32_e32 v2, v4, v188
	v_fmac_f32_e32 v2, v6, v190
	v_fmac_f32_e32 v2, v7, v191
	ds_read_b128 v[188:191], v43 offset:48304
	s_waitcnt lgkmcnt(7)
	v_mul_f32_e32 v3, v9, v193
	v_fmac_f32_e32 v3, v8, v192
	v_fmac_f32_e32 v3, v10, v194
	v_add_f32_e32 v2, 0, v2
	v_fmac_f32_e32 v3, v11, v195
	v_add_f32_e32 v2, v2, v3
	s_waitcnt lgkmcnt(6)
	v_mul_f32_e32 v3, v13, v197
	v_fmac_f32_e32 v3, v12, v196
	v_fmac_f32_e32 v3, v14, v198
	v_fmac_f32_e32 v3, v15, v199
	ds_read_b128 v[192:195], v43 offset:48336
	v_add_f32_e32 v2, v2, v3
	s_waitcnt lgkmcnt(6)
	v_mul_f32_e32 v3, v17, v173
	v_fmac_f32_e32 v3, v16, v172
	v_fmac_f32_e32 v3, v66, v174
	v_fmac_f32_e32 v3, v67, v175
	ds_read_b128 v[196:199], v43 offset:48368
	v_add_f32_e32 v2, v2, v3
	s_waitcnt lgkmcnt(6)
	v_mul_f32_e32 v3, v69, v177
	v_fmac_f32_e32 v3, v68, v176
	v_fmac_f32_e32 v3, v70, v178
	v_fmac_f32_e32 v3, v71, v179
	ds_read_b128 v[172:175], v43 offset:48400
	v_add_f32_e32 v2, v2, v3
	s_waitcnt lgkmcnt(6)
	v_mul_f32_e32 v3, v73, v201
	v_fmac_f32_e32 v3, v72, v200
	v_fmac_f32_e32 v3, v90, v202
	v_fmac_f32_e32 v3, v91, v203
	ds_read_b128 v[176:179], v43 offset:48432
	v_add_f32_e32 v2, v2, v3
	s_waitcnt lgkmcnt(6)
	v_mul_f32_e32 v3, v181, v93
	v_fmac_f32_e32 v3, v180, v92
	v_fmac_f32_e32 v3, v182, v94
	v_fmac_f32_e32 v3, v183, v95
	v_add_f32_e32 v96, v2, v3
	ds_read2st64_b32 v[208:209], v42 offset0:58 offset1:59
	ds_read_b128 v[200:203], v43 offset:48464
	v_add_f32_dpp v96, v96, v96 quad_perm:[1, 0, 3, 2] row_mask:0xf bank_mask:0xf bound_ctrl:1
	v_sub_f32_e32 v96, v206, v96
	s_waitcnt lgkmcnt(7)
	v_mul_f32_e32 v2, v5, v185
	v_fmac_f32_e32 v2, v4, v184
	v_fmac_f32_e32 v2, v6, v186
	v_fmac_f32_e32 v2, v7, v187
	ds_read_b128 v[180:183], v43 offset:48496
	v_add_f32_e32 v2, 0, v2
	v_cndmask_b32_e64 v97, 0, v96, s[46:47]
	s_waitcnt lgkmcnt(7)
	v_mul_f32_e32 v99, v9, v189
	v_fmac_f32_e32 v99, v8, v188
	v_fmac_f32_e32 v99, v10, v190
	v_fmac_f32_e32 v99, v11, v191
	v_add_f32_e32 v2, v2, v99
	ds_read_b128 v[184:187], v43 offset:48544
	s_waitcnt lgkmcnt(7)
	v_mul_f32_e32 v99, v13, v193
	v_fmac_f32_e32 v99, v12, v192
	v_fmac_f32_e32 v99, v14, v194
	v_fmac_f32_e32 v99, v15, v195
	v_add_f32_e32 v2, v2, v99
	ds_read_b128 v[188:191], v43 offset:48576
	s_waitcnt lgkmcnt(7)
	v_mul_f32_e32 v99, v17, v197
	v_fmac_f32_e32 v99, v16, v196
	v_fmac_f32_e32 v99, v66, v198
	v_fmac_f32_e32 v99, v67, v199
	v_add_f32_e32 v2, v2, v99
	ds_read_b128 v[192:195], v43 offset:48608
	s_waitcnt lgkmcnt(7)
	v_mul_f32_e32 v99, v69, v173
	v_fmac_f32_e32 v99, v68, v172
	v_fmac_f32_e32 v99, v70, v174
	v_fmac_f32_e32 v99, v71, v175
	v_add_f32_e32 v2, v2, v99
	ds_read_b128 v[196:199], v43 offset:48640
	s_waitcnt lgkmcnt(7)
	v_mul_f32_e32 v99, v73, v177
	v_fmac_f32_e32 v99, v72, v176
	v_fmac_f32_e32 v99, v90, v178
	v_fmac_f32_e32 v99, v91, v179
	v_add_f32_e32 v2, v2, v99
	ds_read_b128 v[172:175], v43 offset:48672
	s_waitcnt lgkmcnt(6)
	v_mul_f32_e32 v99, v201, v93
	v_fmac_f32_e32 v99, v200, v92
	v_fmac_f32_e32 v99, v202, v94
	v_fmac_f32_e32 v99, v203, v95
	v_add_f32_e32 v2, v2, v99
	ds_read_b128 v[176:179], v43 offset:48704
	ds_read_b128 v[200:203], v43 offset:48736
	s_waitcnt lgkmcnt(7)
	v_mul_f32_e32 v98, v180, v97
	v_fmac_f32_e32 v98, 0, v181
	v_fmac_f32_e32 v98, 0, v182
	v_fmac_f32_e32 v98, 0, v183
	ds_read_b128 v[180:183], v43 offset:48768
	v_add_f32_e32 v2, v2, v98
	s_nop 1
	v_add_f32_dpp v2, v2, v2 quad_perm:[1, 0, 3, 2] row_mask:0xf bank_mask:0xf bound_ctrl:1
	v_sub_f32_e32 v98, v207, v2
	s_waitcnt lgkmcnt(7)
	v_mul_f32_e32 v2, v5, v185
	v_fmac_f32_e32 v2, v4, v184
	v_fmac_f32_e32 v2, v6, v186
	v_fmac_f32_e32 v2, v7, v187
	ds_read_b128 v[184:187], v43 offset:48816
	s_waitcnt lgkmcnt(7)
	v_mul_f32_e32 v3, v9, v189
	v_fmac_f32_e32 v3, v8, v188
	v_fmac_f32_e32 v3, v10, v190
	v_add_f32_e32 v2, 0, v2
	v_fmac_f32_e32 v3, v11, v191
	v_add_f32_e32 v2, v2, v3
	s_waitcnt lgkmcnt(6)
	v_mul_f32_e32 v3, v13, v193
	v_fmac_f32_e32 v3, v12, v192
	v_fmac_f32_e32 v3, v14, v194
	v_fmac_f32_e32 v3, v15, v195
	ds_read_b128 v[188:191], v43 offset:48848
	v_add_f32_e32 v2, v2, v3
	v_cndmask_b32_e64 v102, 0, v98, s[46:47]
	s_waitcnt lgkmcnt(6)
	v_mul_f32_e32 v3, v17, v197
	v_fmac_f32_e32 v3, v16, v196
	v_fmac_f32_e32 v3, v66, v198
	v_fmac_f32_e32 v3, v67, v199
	ds_read_b128 v[192:195], v43 offset:48880
	v_add_f32_e32 v2, v2, v3
	s_waitcnt lgkmcnt(6)
	v_mul_f32_e32 v3, v69, v173
	v_fmac_f32_e32 v3, v68, v172
	v_fmac_f32_e32 v3, v70, v174
	v_fmac_f32_e32 v3, v71, v175
	ds_read_b128 v[196:199], v43 offset:48912
	v_add_f32_e32 v2, v2, v3
	s_waitcnt lgkmcnt(6)
	v_mul_f32_e32 v3, v73, v177
	v_fmac_f32_e32 v3, v72, v176
	v_fmac_f32_e32 v3, v90, v178
	v_fmac_f32_e32 v3, v91, v179
	ds_read_b128 v[172:175], v43 offset:48944
	v_add_f32_e32 v2, v2, v3
	s_waitcnt lgkmcnt(6)
	v_mul_f32_e32 v3, v201, v93
	v_fmac_f32_e32 v3, v200, v92
	v_fmac_f32_e32 v3, v202, v94
	v_fmac_f32_e32 v3, v203, v95
	ds_read_b128 v[176:179], v43 offset:48976
	v_add_f32_e32 v2, v2, v3
	s_waitcnt lgkmcnt(6)
	v_mul_f32_e32 v3, v181, v102
	v_fmac_f32_e32 v3, v180, v97
	v_fmac_f32_e32 v3, 0, v182
	v_fmac_f32_e32 v3, 0, v183
	v_add_f32_e32 v99, v2, v3
	ds_read2st64_b32 v[204:205], v42 offset0:60 offset1:61
	ds_read_b128 v[200:203], v43 offset:49008
	v_add_f32_dpp v99, v99, v99 quad_perm:[1, 0, 3, 2] row_mask:0xf bank_mask:0xf bound_ctrl:1
	v_sub_f32_e32 v99, v208, v99
	s_waitcnt lgkmcnt(7)
; DI void dn_prep_item(CParams& p, int layer, int it, int S, char* lds) {
;     ...
;     const int c = tid >> 1, half = tid & 1;
;     {
;       const float* Rc = (c < 64) ? (RU + c) : (RW + (c - 64));
;       const float* Ah = Am + 4 * half;
; #pragma unroll
;       for (int i = 0; i < 64; ++i) {
;         float part = 0.f;
; #pragma unroll
;         for (int q = 0; q < (i + 7) / 8; ++q) {
;           const f32x4 a = *(const f32x4*)(Ah + i * 68 + 8 * q);
;           part += a[0] * xs[4 * q] + a[1] * xs[4 * q + 1] + a[2] * xs[4 * q + 2] + a[3] * xs[4 * q + 3];
;         }
;         const float other = __int_as_float(__builtin_amdgcn_update_dpp(0, __float_as_int(part), 0xB1, 0xf, 0xf, true));
;         const float xi = Rc[i * 64] - (part + other);
;         const int loc = ((i >> 3) << 2) + (i & 3);
;         if (((i >> 2) & 1) == 0) xs[loc] = (half == 0) ? xi : xs[loc];
;         else xs[loc] = (half == 1) ? xi : xs[loc];
;         if (i < 16 ? ((i & 7) == 7) : (i < 32 ? ((i & 3) == 3) : ((i & 1) == 1))) asm volatile("" ::: "memory");
;       }
;     }
	v_mul_f32_e32 v2, v5, v185
	v_fmac_f32_e32 v2, v4, v184
	v_fmac_f32_e32 v2, v6, v186
	v_fmac_f32_e32 v2, v7, v187
	ds_read_b128 v[180:183], v43 offset:49040
	v_add_f32_e32 v2, 0, v2
	v_cndmask_b32_e64 v103, 0, v99, s[46:47]
	s_waitcnt lgkmcnt(7)
	v_mul_f32_e32 v100, v9, v189
	v_fmac_f32_e32 v100, v8, v188
	v_fmac_f32_e32 v100, v10, v190
	v_fmac_f32_e32 v100, v11, v191
	ds_read_b128 v[184:187], v43 offset:49088
	v_add_f32_e32 v2, v2, v100
	s_waitcnt lgkmcnt(7)
	v_mul_f32_e32 v100, v13, v193
	v_fmac_f32_e32 v100, v12, v192
	v_fmac_f32_e32 v100, v14, v194
	v_fmac_f32_e32 v100, v15, v195
	ds_read_b128 v[188:191], v43 offset:49120
	v_add_f32_e32 v2, v2, v100
	s_waitcnt lgkmcnt(7)
	v_mul_f32_e32 v100, v17, v197
	v_fmac_f32_e32 v100, v16, v196
	v_fmac_f32_e32 v100, v66, v198
	v_fmac_f32_e32 v100, v67, v199
	ds_read_b128 v[192:195], v43 offset:49152
	v_add_f32_e32 v2, v2, v100
	s_waitcnt lgkmcnt(7)
	v_mul_f32_e32 v100, v69, v173
	v_fmac_f32_e32 v100, v68, v172
	v_fmac_f32_e32 v100, v70, v174
	v_fmac_f32_e32 v100, v71, v175
	ds_read_b128 v[196:199], v43 offset:49184
	v_add_f32_e32 v2, v2, v100
	s_waitcnt lgkmcnt(7)
	v_mul_f32_e32 v100, v73, v177
	v_fmac_f32_e32 v100, v72, v176
	v_fmac_f32_e32 v100, v90, v178
	v_fmac_f32_e32 v100, v91, v179
	ds_read_b128 v[172:175], v43 offset:49216
	v_add_f32_e32 v2, v2, v100
	s_waitcnt lgkmcnt(6)
	v_mul_f32_e32 v100, v201, v93
	v_fmac_f32_e32 v100, v92, v200
	v_fmac_f32_e32 v100, v202, v94
	v_fmac_f32_e32 v100, v203, v95
	ds_read_b128 v[176:179], v43 offset:49248
	v_add_f32_e32 v2, v2, v100
	s_waitcnt lgkmcnt(6)
	v_mul_f32_e32 v100, v181, v102
	v_fmac_f32_e32 v100, v180, v97
	v_fmac_f32_e32 v100, v182, v103
	v_fmac_f32_e32 v100, 0, v183
	ds_read_b128 v[200:203], v43 offset:49280
	ds_read_b128 v[180:183], v43 offset:49312
	v_add_f32_e32 v2, v2, v100
	s_nop 1
	v_add_f32_dpp v2, v2, v2 quad_perm:[1, 0, 3, 2] row_mask:0xf bank_mask:0xf bound_ctrl:1
	v_sub_f32_e32 v100, v209, v2
	s_waitcnt lgkmcnt(7)
	v_mul_f32_e32 v2, v5, v185
	v_fmac_f32_e32 v2, v4, v184
	v_fmac_f32_e32 v2, v6, v186
	v_fmac_f32_e32 v2, v7, v187
	ds_read_b128 v[184:187], v43 offset:49360
	s_waitcnt lgkmcnt(7)
	v_mul_f32_e32 v3, v9, v189
	v_fmac_f32_e32 v3, v8, v188
	v_fmac_f32_e32 v3, v10, v190
	v_add_f32_e32 v2, 0, v2
	v_fmac_f32_e32 v3, v11, v191
	v_add_f32_e32 v2, v2, v3
	s_waitcnt lgkmcnt(6)
	v_mul_f32_e32 v3, v13, v193
	v_fmac_f32_e32 v3, v12, v192
	v_fmac_f32_e32 v3, v14, v194
	v_fmac_f32_e32 v3, v15, v195
	ds_read_b128 v[188:191], v43 offset:49392
	v_add_f32_e32 v2, v2, v3
	v_cndmask_b32_e64 v101, 0, v100, s[46:47]
	s_waitcnt lgkmcnt(6)
	v_mul_f32_e32 v3, v17, v197
	v_fmac_f32_e32 v3, v16, v196
	v_fmac_f32_e32 v3, v66, v198
	v_fmac_f32_e32 v3, v67, v199
	ds_read_b128 v[192:195], v43 offset:49424
	v_add_f32_e32 v2, v2, v3
	s_waitcnt lgkmcnt(6)
	v_mul_f32_e32 v3, v69, v173
	v_fmac_f32_e32 v3, v68, v172
	v_fmac_f32_e32 v3, v70, v174
	v_fmac_f32_e32 v3, v71, v175
	ds_read_b128 v[196:199], v43 offset:49456
	v_add_f32_e32 v2, v2, v3
	s_waitcnt lgkmcnt(6)
	v_mul_f32_e32 v3, v73, v177
	v_fmac_f32_e32 v3, v72, v176
	v_fmac_f32_e32 v3, v90, v178
	v_fmac_f32_e32 v3, v91, v179
	ds_read_b128 v[172:175], v43 offset:49488
	v_add_f32_e32 v2, v2, v3
	s_waitcnt lgkmcnt(6)
	v_mul_f32_e32 v3, v93, v201
	v_fmac_f32_e32 v3, v92, v200
	v_fmac_f32_e32 v3, v202, v94
	v_fmac_f32_e32 v3, v203, v95
	ds_read_b128 v[176:179], v43 offset:49520
	v_add_f32_e32 v2, v2, v3
	s_waitcnt lgkmcnt(6)
	v_mul_f32_e32 v3, v181, v102
	v_fmac_f32_e32 v3, v180, v97
	v_fmac_f32_e32 v3, v182, v103
	v_fmac_f32_e32 v3, v183, v101
	v_add_f32_e32 v97, v2, v3
	ds_read2st64_b32 v[206:207], v42 offset0:62 offset1:63
	ds_read_b128 v[200:203], v43 offset:49552
	v_add_f32_dpp v97, v97, v97 quad_perm:[1, 0, 3, 2] row_mask:0xf bank_mask:0xf bound_ctrl:1
	v_sub_f32_e32 v2, v204, v97
	v_cndmask_b32_e64 v96, v2, v96, s[46:47]
	s_waitcnt lgkmcnt(7)
	v_mul_f32_e32 v2, v5, v185
	v_fmac_f32_e32 v2, v4, v184
	v_fmac_f32_e32 v2, v6, v186
	v_fmac_f32_e32 v2, v7, v187
	ds_read_b128 v[180:183], v43 offset:49584
	v_add_f32_e32 v2, 0, v2
	s_waitcnt lgkmcnt(7)
	v_mul_f32_e32 v97, v9, v189
	v_fmac_f32_e32 v97, v8, v188
	v_fmac_f32_e32 v97, v10, v190
	v_fmac_f32_e32 v97, v11, v191
	ds_read_b128 v[184:187], v43 offset:49632
	v_add_f32_e32 v2, v2, v97
	s_waitcnt lgkmcnt(7)
	v_mul_f32_e32 v97, v13, v193
	v_fmac_f32_e32 v97, v12, v192
	v_fmac_f32_e32 v97, v14, v194
	v_fmac_f32_e32 v97, v15, v195
	ds_read_b128 v[188:191], v43 offset:49664
	v_add_f32_e32 v2, v2, v97
	s_waitcnt lgkmcnt(7)
	v_mul_f32_e32 v97, v17, v197
	v_fmac_f32_e32 v97, v16, v196
	v_fmac_f32_e32 v97, v66, v198
	v_fmac_f32_e32 v97, v67, v199
	ds_read_b128 v[192:195], v43 offset:49696
	v_add_f32_e32 v2, v2, v97
	s_waitcnt lgkmcnt(7)
	v_mul_f32_e32 v97, v69, v173
	v_fmac_f32_e32 v97, v68, v172
	v_fmac_f32_e32 v97, v70, v174
	v_fmac_f32_e32 v97, v71, v175
	ds_read_b128 v[196:199], v43 offset:49728
	v_add_f32_e32 v2, v2, v97
	s_waitcnt lgkmcnt(7)
	v_mul_f32_e32 v97, v73, v177
	v_fmac_f32_e32 v97, v72, v176
	v_fmac_f32_e32 v97, v90, v178
	v_fmac_f32_e32 v97, v91, v179
	ds_read_b128 v[172:175], v43 offset:49760
	v_add_f32_e32 v2, v2, v97
	s_waitcnt lgkmcnt(6)
	v_mul_f32_e32 v97, v93, v201
	v_fmac_f32_e32 v97, v92, v200
	v_fmac_f32_e32 v97, v94, v202
	v_fmac_f32_e32 v97, v95, v203
	ds_read_b128 v[176:179], v43 offset:49792
	v_add_f32_e32 v2, v2, v97
	s_waitcnt lgkmcnt(6)
	v_mul_f32_e32 v97, v180, v96
	v_fmac_f32_e32 v97, v181, v102
	v_fmac_f32_e32 v97, v182, v103
	v_fmac_f32_e32 v97, v183, v101
	ds_read_b128 v[200:203], v43 offset:49824
	ds_read_b128 v[180:183], v43 offset:49856
	v_add_f32_e32 v2, v2, v97
	s_nop 1
	v_add_f32_dpp v2, v2, v2 quad_perm:[1, 0, 3, 2] row_mask:0xf bank_mask:0xf bound_ctrl:1
	v_sub_f32_e32 v2, v205, v2
	v_cndmask_b32_e64 v97, v2, v98, s[46:47]
	s_waitcnt lgkmcnt(7)
; DI void dn_prep_item(CParams& p, int layer, int it, int S, char* lds) {
;     ...
;     const int c = tid >> 1, half = tid & 1;
;     {
;       const float* Rc = (c < 64) ? (RU + c) : (RW + (c - 64));
;       const float* Ah = Am + 4 * half;
; #pragma unroll
;       for (int i = 0; i < 64; ++i) {
;         float part = 0.f;
; #pragma unroll
;         for (int q = 0; q < (i + 7) / 8; ++q) {
;           const f32x4 a = *(const f32x4*)(Ah + i * 68 + 8 * q);
;           part += a[0] * xs[4 * q] + a[1] * xs[4 * q + 1] + a[2] * xs[4 * q + 2] + a[3] * xs[4 * q + 3];
;         }
;         const float other = __int_as_float(__builtin_amdgcn_update_dpp(0, __float_as_int(part), 0xB1, 0xf, 0xf, true));
;         const float xi = Rc[i * 64] - (part + other);
;         const int loc = ((i >> 3) << 2) + (i & 3);
;         if (((i >> 2) & 1) == 0) xs[loc] = (half == 0) ? xi : xs[loc];
;         else xs[loc] = (half == 1) ? xi : xs[loc];
;         if (i < 16 ? ((i & 7) == 7) : (i < 32 ? ((i & 3) == 3) : ((i & 1) == 1))) asm volatile("" ::: "memory");
;       }
;     }
	v_mul_f32_e32 v2, v5, v185
	v_fmac_f32_e32 v2, v4, v184
	v_fmac_f32_e32 v2, v6, v186
	v_fmac_f32_e32 v2, v7, v187
	ds_read_b128 v[184:187], v43 offset:49904
	s_waitcnt lgkmcnt(7)
	v_mul_f32_e32 v3, v9, v189
	v_fmac_f32_e32 v3, v8, v188
	v_fmac_f32_e32 v3, v10, v190
	v_add_f32_e32 v2, 0, v2
	v_fmac_f32_e32 v3, v11, v191
	v_add_f32_e32 v2, v2, v3
	s_waitcnt lgkmcnt(6)
	v_mul_f32_e32 v3, v13, v193
	v_fmac_f32_e32 v3, v12, v192
	v_fmac_f32_e32 v3, v14, v194
	v_fmac_f32_e32 v3, v15, v195
	ds_read_b128 v[188:191], v43 offset:49936
	v_add_f32_e32 v2, v2, v3
	s_waitcnt lgkmcnt(6)
	v_mul_f32_e32 v3, v17, v197
	v_fmac_f32_e32 v3, v16, v196
	v_fmac_f32_e32 v3, v66, v198
	v_fmac_f32_e32 v3, v67, v199
	ds_read_b128 v[192:195], v43 offset:49968
	v_add_f32_e32 v2, v2, v3
	s_waitcnt lgkmcnt(6)
	v_mul_f32_e32 v3, v69, v173
	v_fmac_f32_e32 v3, v68, v172
	v_fmac_f32_e32 v3, v70, v174
	v_fmac_f32_e32 v3, v71, v175
	ds_read_b128 v[196:199], v43 offset:50000
	v_add_f32_e32 v2, v2, v3
	s_waitcnt lgkmcnt(6)
	v_mul_f32_e32 v3, v73, v177
	v_fmac_f32_e32 v3, v72, v176
	v_fmac_f32_e32 v3, v90, v178
	v_fmac_f32_e32 v3, v91, v179
	ds_read_b128 v[172:175], v43 offset:50032
	v_add_f32_e32 v2, v2, v3
	s_waitcnt lgkmcnt(6)
	v_mul_f32_e32 v3, v93, v201
	v_fmac_f32_e32 v3, v92, v200
	v_fmac_f32_e32 v3, v94, v202
	v_fmac_f32_e32 v3, v95, v203
	ds_read_b128 v[176:179], v43 offset:50064
	v_add_f32_e32 v2, v2, v3
	s_waitcnt lgkmcnt(6)
	v_mul_f32_e32 v3, v181, v97
	v_fmac_f32_e32 v3, v180, v96
	v_fmac_f32_e32 v3, v182, v103
	v_fmac_f32_e32 v3, v183, v101
	v_add_f32_e32 v98, v2, v3
	ds_read_b128 v[200:203], v43 offset:50096
	s_nop 0
	v_add_f32_dpp v98, v98, v98 quad_perm:[1, 0, 3, 2] row_mask:0xf bank_mask:0xf bound_ctrl:1
	v_sub_f32_e32 v2, v206, v98
	v_cndmask_b32_e64 v98, v2, v99, s[46:47]
	s_waitcnt lgkmcnt(6)
	v_mul_f32_e32 v2, v5, v185
	v_fmac_f32_e32 v2, v4, v184
	v_fmac_f32_e32 v2, v6, v186
	v_fmac_f32_e32 v2, v7, v187
	ds_read_b128 v[180:183], v43 offset:50128
	v_add_f32_e32 v2, 0, v2
	v_cndmask_b32_e64 v4, -v4, v4, s[44:45]
	v_cvt_pk_bf16_f32 v4, v4, s0
	s_waitcnt lgkmcnt(6)
	v_mul_f32_e32 v99, v9, v189
	v_fmac_f32_e32 v99, v8, v188
	v_fmac_f32_e32 v99, v10, v190
	v_fmac_f32_e32 v99, v11, v191
	v_add_f32_e32 v2, v2, v99
	s_waitcnt lgkmcnt(5)
	v_mul_f32_e32 v99, v13, v193
	v_fmac_f32_e32 v99, v12, v192
	v_fmac_f32_e32 v99, v14, v194
	v_fmac_f32_e32 v99, v15, v195
	v_add_f32_e32 v2, v2, v99
	s_waitcnt lgkmcnt(4)
	v_mul_f32_e32 v99, v17, v197
	v_fmac_f32_e32 v99, v16, v196
	v_fmac_f32_e32 v99, v66, v198
	v_fmac_f32_e32 v99, v67, v199
	v_add_f32_e32 v2, v2, v99
	s_waitcnt lgkmcnt(3)
	v_mul_f32_e32 v99, v69, v173
	v_fmac_f32_e32 v99, v68, v172
	v_fmac_f32_e32 v99, v70, v174
	v_fmac_f32_e32 v99, v71, v175
	v_add_f32_e32 v2, v2, v99
	s_waitcnt lgkmcnt(2)
	v_mul_f32_e32 v99, v73, v177
	v_fmac_f32_e32 v99, v72, v176
	v_fmac_f32_e32 v99, v90, v178
	v_fmac_f32_e32 v99, v91, v179
	v_add_f32_e32 v2, v2, v99
	s_waitcnt lgkmcnt(1)
	v_mul_f32_e32 v99, v93, v201
	v_fmac_f32_e32 v99, v92, v200
	v_fmac_f32_e32 v99, v94, v202
	v_fmac_f32_e32 v99, v95, v203
	v_add_f32_e32 v2, v2, v99
	s_waitcnt lgkmcnt(0)
	v_mul_f32_e32 v99, v181, v97
	v_fmac_f32_e32 v99, v180, v96
	v_fmac_f32_e32 v99, v182, v98
	v_fmac_f32_e32 v99, v183, v101
	v_add_f32_e32 v2, v2, v99
	s_nop 1
	v_add_f32_dpp v2, v2, v2 quad_perm:[1, 0, 3, 2] row_mask:0xf bank_mask:0xf bound_ctrl:1
	v_sub_f32_e32 v2, v207, v2
	v_cndmask_b32_e64 v99, v2, v100, s[46:47]
	v_or_b32_e32 v2, s28, v106
	v_mov_b32_e32 v3, v107
	v_lshlrev_b64 v[2:3], s90, v[2:3]
	v_lshl_add_u64 v[2:3], v[2:3], 0, s[38:39]
	v_lshlrev_b64 v[2:3], 14, v[2:3]
	v_lshl_add_u64 v[2:3], v[36:37], 0, v[2:3]
	s_waitcnt lgkmcnt(0)
; DI void dn_prep_item(CParams& p, int layer, int it, int S, char* lds) {
;     ...
;     {
;       bf16_t* UWg = (bf16_t*)(p.ws + DN_UW_OFF) + ((((size_t)bh * 2 + d) * NC + ch) * 8192);
;       const float sgn = (c < 64) ? 1.f : -1.f;
;       bf16_t* dst = UWg + ((c < 64) ? c : (4096 + c - 64));
; #pragma unroll
;       for (int loc = 0; loc < 32; ++loc) {
;         const int i = (((loc >> 2) * 2 + half) << 2) + (loc & 3);
;         dst[i * 64] = f2bf(sgn * xs[loc]);
;       }
;     }
	global_store_short v[2:3], v4, off
	v_cndmask_b32_e64 v4, -v5, v5, s[44:45]
	v_cvt_pk_bf16_f32 v4, v4, s0
	global_store_short v[2:3], v4, off offset:128
	v_cndmask_b32_e64 v4, -v6, v6, s[44:45]
	v_cvt_pk_bf16_f32 v4, v4, s0
	global_store_short v[2:3], v4, off offset:256
	v_cndmask_b32_e64 v4, -v7, v7, s[44:45]
	v_cvt_pk_bf16_f32 v4, v4, s0
	global_store_short v[2:3], v4, off offset:384
	v_cndmask_b32_e64 v4, -v8, v8, s[44:45]
	v_cvt_pk_bf16_f32 v4, v4, s0
	global_store_short v[2:3], v4, off offset:1024
	v_cndmask_b32_e64 v4, -v9, v9, s[44:45]
	v_cvt_pk_bf16_f32 v4, v4, s0
	global_store_short v[2:3], v4, off offset:1152
	v_cndmask_b32_e64 v4, -v10, v10, s[44:45]
	v_cvt_pk_bf16_f32 v4, v4, s0
	global_store_short v[2:3], v4, off offset:1280
	v_cndmask_b32_e64 v4, -v11, v11, s[44:45]
	v_cvt_pk_bf16_f32 v4, v4, s0
	global_store_short v[2:3], v4, off offset:1408
	v_cndmask_b32_e64 v4, -v12, v12, s[44:45]
	v_cvt_pk_bf16_f32 v4, v4, s0
	global_store_short v[2:3], v4, off offset:2048
	v_cndmask_b32_e64 v4, -v13, v13, s[44:45]
	v_cvt_pk_bf16_f32 v4, v4, s0
	global_store_short v[2:3], v4, off offset:2176
	v_cndmask_b32_e64 v4, -v14, v14, s[44:45]
	v_cvt_pk_bf16_f32 v4, v4, s0
	global_store_short v[2:3], v4, off offset:2304
	v_cndmask_b32_e64 v4, -v15, v15, s[44:45]
	v_cvt_pk_bf16_f32 v4, v4, s0
	global_store_short v[2:3], v4, off offset:2432
	v_cndmask_b32_e64 v4, -v16, v16, s[44:45]
	v_cvt_pk_bf16_f32 v4, v4, s0
	global_store_short v[2:3], v4, off offset:3072
	v_cndmask_b32_e64 v4, -v17, v17, s[44:45]
	v_cvt_pk_bf16_f32 v4, v4, s0
	global_store_short v[2:3], v4, off offset:3200
	v_cndmask_b32_e64 v4, -v66, v66, s[44:45]
	v_cvt_pk_bf16_f32 v4, v4, s0
	global_store_short v[2:3], v4, off offset:3328
	v_cndmask_b32_e64 v4, -v67, v67, s[44:45]
	v_cvt_pk_bf16_f32 v4, v4, s0
	global_store_short v[2:3], v4, off offset:3456
	v_cndmask_b32_e64 v4, -v68, v68, s[44:45]
	v_add_co_u32_e32 v2, vcc, s20, v2
	v_cvt_pk_bf16_f32 v4, v4, s0
	s_nop 0
	v_addc_co_u32_e32 v3, vcc, 0, v3, vcc
	global_store_short v[2:3], v4, off
	v_cndmask_b32_e64 v4, -v69, v69, s[44:45]
	v_cvt_pk_bf16_f32 v4, v4, s0
	global_store_short v[2:3], v4, off offset:128
	v_cndmask_b32_e64 v4, -v70, v70, s[44:45]
	v_cvt_pk_bf16_f32 v4, v4, s0
	global_store_short v[2:3], v4, off offset:256
	v_cndmask_b32_e64 v4, -v71, v71, s[44:45]
	v_cvt_pk_bf16_f32 v4, v4, s0
	global_store_short v[2:3], v4, off offset:384
	v_cndmask_b32_e64 v4, -v72, v72, s[44:45]
	v_cvt_pk_bf16_f32 v4, v4, s0
	global_store_short v[2:3], v4, off offset:1024
	v_cndmask_b32_e64 v4, -v73, v73, s[44:45]
	v_cvt_pk_bf16_f32 v4, v4, s0
	global_store_short v[2:3], v4, off offset:1152
	v_cndmask_b32_e64 v4, -v90, v90, s[44:45]
	v_cvt_pk_bf16_f32 v4, v4, s0
	global_store_short v[2:3], v4, off offset:1280
	v_cndmask_b32_e64 v4, -v91, v91, s[44:45]
	v_cvt_pk_bf16_f32 v4, v4, s0
	global_store_short v[2:3], v4, off offset:1408
	v_cndmask_b32_e64 v4, -v92, v92, s[44:45]
	v_cvt_pk_bf16_f32 v4, v4, s0
	global_store_short v[2:3], v4, off offset:2048
	v_cndmask_b32_e64 v4, -v93, v93, s[44:45]
	v_cvt_pk_bf16_f32 v4, v4, s0
	global_store_short v[2:3], v4, off offset:2176
	v_cndmask_b32_e64 v4, -v94, v94, s[44:45]
	v_cvt_pk_bf16_f32 v4, v4, s0
	global_store_short v[2:3], v4, off offset:2304
	v_cndmask_b32_e64 v4, -v95, v95, s[44:45]
	v_cvt_pk_bf16_f32 v4, v4, s0
	global_store_short v[2:3], v4, off offset:2432
	v_cndmask_b32_e64 v4, -v96, v96, s[44:45]
	v_cvt_pk_bf16_f32 v4, v4, s0
	global_store_short v[2:3], v4, off offset:3072
	v_cndmask_b32_e64 v4, -v97, v97, s[44:45]
	v_cvt_pk_bf16_f32 v4, v4, s0
	global_store_short v[2:3], v4, off offset:3200
	v_cndmask_b32_e64 v4, -v98, v98, s[44:45]
	v_cvt_pk_bf16_f32 v4, v4, s0
	global_store_short v[2:3], v4, off offset:3328
	v_cndmask_b32_e64 v4, -v99, v99, s[44:45]
	v_cvt_pk_bf16_f32 v4, v4, s0
	s_mov_b32 s28, 1
	s_and_b64 vcc, exec, s[82:83]
	global_store_short v[2:3], v4, off offset:3456
	s_cbranch_vccnz .LBB0_461
